# v108 with s_setprio 3 instead of 1 for the MFMA blocks of the K-loops
# baseline (speedup 1.0000x reference)
; #define PG8_STAGE(bufoff, gbase, voff) do { _Pragma("unroll") for (int _i = 0; _i < 2; ++_i) \
;         __builtin_amdgcn_global_load_lds((const unsigned*)((const char*)(gbase) + (voff)[_i]), (PG8_LAS unsigned*)(lds + (bufoff) + ldsw + _i * 8192), 16, 0, 0); } while (0)
; #define PG8_LDA(dst, b, h) do { _Pragma("unroll") for (int m = 0; m < 4; ++m) _Pragma("unroll") for (int k = 0; k < 2; ++k) dst[m][k] = *(const PG8_LAS bf16x8*)(lds + PG8_SA(b, h) + aoff + m * 2048 + k * 1024); } while (0)
; #define PG8_LDB(dst, b, h) do { _Pragma("unroll") for (int n = 0; n < 2; ++n) _Pragma("unroll") for (int k = 0; k < 2; ++k) dst[n][k] = *(const PG8_LAS bf16x8*)(lds + PG8_SB(b, h) + boff + n * 2048 + k * 1024); } while (0)
; #define PG8_WAIT_V(n) asm volatile("s_waitcnt vmcnt(" #n ")" ::: "memory")
; #define PG8_WAIT_L(n) asm volatile("s_waitcnt lgkmcnt(" #n ")" ::: "memory")
; #define PG8_BAR __builtin_amdgcn_s_barrier()
; #define PG8_SCHED __builtin_amdgcn_sched_barrier(0)
; template <class Epi, class Sched, bool ALIGN_EPI = false, bool SP2 = false>
; __device__ __forceinline__ void gemm_phase(PG8_LAS unsigned char* lds, const Gemm g, const Sched& S, const Epi& E) {
;     ...
;         const char* nA = has_next ? (const char*)g.A + (size_t)nxt.pm * tstep : cA; const char* nB = has_next ? (const char*)g.Bt + (size_t)nxt.pn * tstep : cB;
;         for (int t = 0; t < nt; t += 2) {
;             const bool last = (t == nt - 2);
;             const char* a1 = cA + (size_t)(t + 1) * kstep;
;             const char* a2 = last ? nA : cA + (size_t)(t + 2) * kstep; const char* b2 = last ? nB : cB + (size_t)(t + 2) * kstep;
;             const char* a3 = a2 + kstep; const char* b3 = b2 + kstep;
;             if (last && has_next) S.a_ready(nxt);
;             if constexpr (SP2) {
;             PG8_LDB(B0, 0, 0); PG8_LDB(B1, 0, 1); PG8_SCHED; PG8_LDA(At, 0, 0); PG8_STAGE(PG8_SA(1, 1), a1 + hstep, voffA);
;             PG8_WAIT_V(8); PG8_WAIT_L(0); PG8_BAR; PG8_MMA(0, 0, At, B0); PG8_MMA(0, 1, At, B1); PG8_BAR; PG8_SCHED;
;             PG8_LDA(At, 0, 1); PG8_STAGE(PG8_SB(0, 0), b2, voffB); PG8_STAGE(PG8_SB(0, 1), b2 + hstep, voffB); PG8_STAGE(PG8_SA(0, 0), a2, voffA);
;             PG8_WAIT_V(8); PG8_WAIT_L(0); PG8_BAR; PG8_MMA(1, 0, At, B0); PG8_MMA(1, 1, At, B1); PG8_BAR; PG8_SCHED;
.LBB0_99:
	s_ashr_i32 s21, s20, 31
	s_lshl_b64 s[24:25], s[20:21], 19
	s_add_u32 s24, s35, s24
	s_addc_u32 s25, s38, s25
	s_and_b64 s[26:27], s[4:5], exec
	s_cselect_b32 s3, s25, s9
	s_cselect_b32 s7, s24, s8
	s_ashr_i32 s23, s22, 31
	s_lshl_b64 s[26:27], s[22:23], 19
	s_add_u32 s26, s39, s26
	s_addc_u32 s27, s40, s27
	s_and_b64 s[30:31], s[4:5], exec
	s_cselect_b32 s11, s27, s29
	s_cselect_b32 s21, s26, s28
	s_add_u32 s8, s8, 0x40080
	s_addc_u32 s9, s9, 0
	s_add_u32 s23, s28, 0x100
	s_addc_u32 s44, s29, 0
	s_mov_b32 s45, -2
	s_add_u32 s28, s8, 0xfffc0080
	s_addc_u32 s29, s9, -1
	s_cmp_eq_u32 s45, 12
	s_cselect_b32 s31, s3, s29
	s_cselect_b32 s30, s7, s28
	s_cselect_b32 s29, s11, s44
	s_cselect_b32 s28, s21, s23
	ds_read_b128 v[132:135], v204
	ds_read_b128 v[136:139], v204 offset:1024
	ds_read_b128 v[140:143], v204 offset:2048
	ds_read_b128 v[144:147], v204 offset:3072
	ds_read_b128 v[148:151], v204 offset:16384
	ds_read_b128 v[152:155], v204 offset:17408
	ds_read_b128 v[156:159], v204 offset:18432
	ds_read_b128 v[160:163], v204 offset:19456
	v_lshl_add_u64 v[194:195], s[8:9], 0, v[178:179]
	s_add_i32 m0, s42, 0xc000
	ds_read_b128 v[164:167], v205
	ds_read_b128 v[182:185], v205 offset:1024
	ds_read_b128 v[186:189], v205 offset:2048
	ds_read_b128 v[190:193], v205 offset:3072
	ds_read_b128 v[208:211], v205 offset:4096
	ds_read_b128 v[212:215], v205 offset:5120
	ds_read_b128 v[216:219], v205 offset:6144
	ds_read_b128 v[220:223], v205 offset:7168
	global_load_lds_dwordx4 v[194:195], off
	s_add_i32 m0, s42, 0xe000
	v_lshl_add_u64 v[194:195], s[8:9], 0, v[180:181]
	global_load_lds_dwordx4 v[194:195], off
	s_waitcnt vmcnt(8) lgkmcnt(0)
	s_barrier
	s_setprio 3
	v_mfma_f32_16x16x32_bf16 v[128:131], v[132:135], v[164:167], 0
	v_mfma_f32_16x16x32_bf16 v[124:127], v[140:143], v[164:167], 0
	v_mfma_f32_16x16x32_bf16 v[112:115], v[132:135], v[186:189], 0
	v_mfma_f32_16x16x32_bf16 v[108:111], v[140:143], v[186:189], 0
	v_mfma_f32_16x16x32_bf16 v[96:99], v[132:135], v[208:211], 0
	v_mfma_f32_16x16x32_bf16 v[92:95], v[140:143], v[208:211], 0
	v_mfma_f32_16x16x32_bf16 v[80:83], v[132:135], v[216:219], 0
	v_mfma_f32_16x16x32_bf16 v[76:79], v[140:143], v[216:219], 0
	v_mfma_f32_16x16x32_bf16 v[128:131], v[136:139], v[182:185], v[128:131]
	v_mfma_f32_16x16x32_bf16 v[124:127], v[144:147], v[182:185], v[124:127]
	v_mfma_f32_16x16x32_bf16 v[112:115], v[136:139], v[190:193], v[112:115]
	v_mfma_f32_16x16x32_bf16 v[108:111], v[144:147], v[190:193], v[108:111]
	v_mfma_f32_16x16x32_bf16 v[96:99], v[136:139], v[212:215], v[96:99]
	v_mfma_f32_16x16x32_bf16 v[92:95], v[144:147], v[212:215], v[92:95]
	v_mfma_f32_16x16x32_bf16 v[80:83], v[136:139], v[220:223], v[80:83]
	v_mfma_f32_16x16x32_bf16 v[76:79], v[144:147], v[220:223], v[76:79]
	s_setprio 0
	s_setprio 3
	v_mfma_f32_16x16x32_bf16 v[120:123], v[148:151], v[164:167], 0
	v_mfma_f32_16x16x32_bf16 v[116:119], v[156:159], v[164:167], 0
	v_mfma_f32_16x16x32_bf16 v[104:107], v[148:151], v[186:189], 0
	v_mfma_f32_16x16x32_bf16 v[100:103], v[156:159], v[186:189], 0
	v_mfma_f32_16x16x32_bf16 v[88:91], v[148:151], v[208:211], 0
	v_mfma_f32_16x16x32_bf16 v[84:87], v[156:159], v[208:211], 0
	v_mfma_f32_16x16x32_bf16 v[72:75], v[148:151], v[216:219], 0
	v_mfma_f32_16x16x32_bf16 v[68:71], v[156:159], v[216:219], 0
	v_mfma_f32_16x16x32_bf16 v[120:123], v[152:155], v[182:185], v[120:123]
	v_mfma_f32_16x16x32_bf16 v[116:119], v[160:163], v[182:185], v[116:119]
	v_mfma_f32_16x16x32_bf16 v[104:107], v[152:155], v[190:193], v[104:107]
	v_mfma_f32_16x16x32_bf16 v[100:103], v[160:163], v[190:193], v[100:103]
	v_mfma_f32_16x16x32_bf16 v[88:91], v[152:155], v[212:215], v[88:91]
	v_mfma_f32_16x16x32_bf16 v[84:87], v[160:163], v[212:215], v[84:87]
	v_mfma_f32_16x16x32_bf16 v[72:75], v[152:155], v[220:223], v[72:75]
	v_mfma_f32_16x16x32_bf16 v[68:71], v[160:163], v[220:223], v[68:71]
	s_setprio 0
	s_barrier
	v_lshl_add_u64 v[194:195], s[28:29], 0, v[168:169]
	s_add_i32 m0, s41, 0x10000
	ds_read_b128 v[164:167], v205 offset:16384
	ds_read_b128 v[182:185], v205 offset:17408
	ds_read_b128 v[186:189], v205 offset:18432
	ds_read_b128 v[190:193], v205 offset:19456
	ds_read_b128 v[208:211], v205 offset:20480
	ds_read_b128 v[212:215], v205 offset:21504
	ds_read_b128 v[216:219], v205 offset:22528
	ds_read_b128 v[220:223], v205 offset:23552
	global_load_lds_dwordx4 v[194:195], off
	s_add_i32 m0, s41, 0x12000
	s_add_u32 s54, s28, 0x40000
	v_lshl_add_u64 v[202:203], s[28:29], 0, v[172:173]
	s_addc_u32 s55, s29, 0
	global_load_lds_dwordx4 v[202:203], off
	v_lshl_add_u64 v[244:245], s[54:55], 0, v[168:169]
	s_add_i32 m0, s41, 0x14000
	v_lshl_add_u64 v[226:227], s[30:31], 0, v[170:171]
	global_load_lds_dwordx4 v[244:245], off
	s_add_i32 m0, s41, 0x16000
	v_lshl_add_u64 v[246:247], s[54:55], 0, v[172:173]
	global_load_lds_dwordx4 v[246:247], off
	v_lshl_add_u64 v[224:225], s[30:31], 0, v[0:1]
	s_waitcnt vmcnt(6) lgkmcnt(0)
	s_barrier
; #define PG8_STAGE(bufoff, gbase, voff) do { _Pragma("unroll") for (int _i = 0; _i < 2; ++_i) \
;         __builtin_amdgcn_global_load_lds((const unsigned*)((const char*)(gbase) + (voff)[_i]), (PG8_LAS unsigned*)(lds + (bufoff) + ldsw + _i * 8192), 16, 0, 0); } while (0)
; #define PG8_LDA(dst, b, h) do { _Pragma("unroll") for (int m = 0; m < 4; ++m) _Pragma("unroll") for (int k = 0; k < 2; ++k) dst[m][k] = *(const PG8_LAS bf16x8*)(lds + PG8_SA(b, h) + aoff + m * 2048 + k * 1024); } while (0)
; #define PG8_LDB(dst, b, h) do { _Pragma("unroll") for (int n = 0; n < 2; ++n) _Pragma("unroll") for (int k = 0; k < 2; ++k) dst[n][k] = *(const PG8_LAS bf16x8*)(lds + PG8_SB(b, h) + boff + n * 2048 + k * 1024); } while (0)
; #define PG8_MMA(ai, bj, At, Bt) do { __builtin_amdgcn_s_setprio(1); _Pragma("unroll") for (int m = 0; m < 4; ++m) _Pragma("unroll") for (int n = 0; n < 2; ++n) _Pragma("unroll") for (int k = 0; k < 2; ++k) \
;         acc[ai][bj][m][n] = __builtin_amdgcn_mfma_f32_16x16x32_bf16(Bt[n][k], At[m][k], acc[ai][bj][m][n], 0, 0, 0); __builtin_amdgcn_s_setprio(0); } while (0)
; #define PG8_WAIT_V(n) asm volatile("s_waitcnt vmcnt(" #n ")" ::: "memory")
; #define PG8_WAIT_L(n) asm volatile("s_waitcnt lgkmcnt(" #n ")" ::: "memory")
; #define PG8_BAR __builtin_amdgcn_s_barrier()
; #define PG8_SCHED __builtin_amdgcn_sched_barrier(0)
; template <class Epi, class Sched, bool ALIGN_EPI = false, bool SP2 = false>
; __device__ __forceinline__ void gemm_phase(PG8_LAS unsigned char* lds, const Gemm g, const Sched& S, const Epi& E) {
;     ...
;             PG8_LDB(B0, 0, 0); PG8_LDB(B1, 0, 1); PG8_SCHED; PG8_LDA(At, 0, 0); PG8_STAGE(PG8_SA(1, 1), a1 + hstep, voffA);
;             PG8_WAIT_V(8); PG8_WAIT_L(0); PG8_BAR; PG8_MMA(0, 0, At, B0); PG8_MMA(0, 1, At, B1); PG8_BAR; PG8_SCHED;
;             PG8_LDA(At, 0, 1); PG8_STAGE(PG8_SB(0, 0), b2, voffB); PG8_STAGE(PG8_SB(0, 1), b2 + hstep, voffB); PG8_STAGE(PG8_SA(0, 0), a2, voffA);
;             PG8_WAIT_V(8); PG8_WAIT_L(0); PG8_BAR; PG8_MMA(1, 0, At, B0); PG8_MMA(1, 1, At, B1); PG8_BAR; PG8_SCHED;
	s_setprio 3
	v_mfma_f32_16x16x32_bf16 v[64:67], v[132:135], v[164:167], 0
	v_mfma_f32_16x16x32_bf16 v[60:63], v[140:143], v[164:167], 0
	v_mfma_f32_16x16x32_bf16 v[48:51], v[132:135], v[186:189], 0
	v_mfma_f32_16x16x32_bf16 v[44:47], v[140:143], v[186:189], 0
	v_mfma_f32_16x16x32_bf16 v[32:35], v[132:135], v[208:211], 0
	v_mfma_f32_16x16x32_bf16 v[28:31], v[140:143], v[208:211], 0
	v_mfma_f32_16x16x32_bf16 v[16:19], v[132:135], v[216:219], 0
	v_mfma_f32_16x16x32_bf16 v[12:15], v[140:143], v[216:219], 0
	v_mfma_f32_16x16x32_bf16 v[64:67], v[136:139], v[182:185], v[64:67]
	v_mfma_f32_16x16x32_bf16 v[60:63], v[144:147], v[182:185], v[60:63]
	v_mfma_f32_16x16x32_bf16 v[48:51], v[136:139], v[190:193], v[48:51]
	v_mfma_f32_16x16x32_bf16 v[44:47], v[144:147], v[190:193], v[44:47]
	v_mfma_f32_16x16x32_bf16 v[32:35], v[136:139], v[212:215], v[32:35]
	v_mfma_f32_16x16x32_bf16 v[28:31], v[144:147], v[212:215], v[28:31]
	v_mfma_f32_16x16x32_bf16 v[16:19], v[136:139], v[220:223], v[16:19]
	v_mfma_f32_16x16x32_bf16 v[12:15], v[144:147], v[220:223], v[12:15]
	s_setprio 0
	s_setprio 3
	v_mfma_f32_16x16x32_bf16 v[56:59], v[148:151], v[164:167], 0
	v_mfma_f32_16x16x32_bf16 v[52:55], v[156:159], v[164:167], 0
	v_mfma_f32_16x16x32_bf16 v[40:43], v[148:151], v[186:189], 0
	v_mfma_f32_16x16x32_bf16 v[36:39], v[156:159], v[186:189], 0
	v_mfma_f32_16x16x32_bf16 v[24:27], v[148:151], v[208:211], 0
	v_mfma_f32_16x16x32_bf16 v[20:23], v[156:159], v[208:211], 0
	v_mfma_f32_16x16x32_bf16 v[8:11], v[148:151], v[216:219], 0
	v_mfma_f32_16x16x32_bf16 v[4:7], v[156:159], v[216:219], 0
	v_mfma_f32_16x16x32_bf16 v[56:59], v[152:155], v[182:185], v[56:59]
	v_mfma_f32_16x16x32_bf16 v[52:55], v[160:163], v[182:185], v[52:55]
	v_mfma_f32_16x16x32_bf16 v[40:43], v[152:155], v[190:193], v[40:43]
	v_mfma_f32_16x16x32_bf16 v[36:39], v[160:163], v[190:193], v[36:39]
	v_mfma_f32_16x16x32_bf16 v[24:27], v[152:155], v[212:215], v[24:27]
	v_mfma_f32_16x16x32_bf16 v[20:23], v[160:163], v[212:215], v[20:23]
	v_mfma_f32_16x16x32_bf16 v[8:11], v[152:155], v[220:223], v[8:11]
	v_mfma_f32_16x16x32_bf16 v[4:7], v[160:163], v[220:223], v[4:7]
	s_setprio 0
	s_barrier
	s_branch .Lkmid_0
.LBB0_100:
	s_add_u32 s28, s8, 0xfffc0080
	s_addc_u32 s29, s9, -1
	s_cmp_eq_u32 s45, 12
	s_cselect_b32 s31, s3, s29
	s_cselect_b32 s30, s7, s28
	s_cselect_b32 s29, s11, s44
	s_cselect_b32 s28, s21, s23
	s_add_i32 m0, s50, 0xffffff80
	ds_read_b128 v[132:135], v204
	ds_read_b128 v[136:139], v204 offset:1024
	ds_read_b128 v[140:143], v204 offset:2048
	ds_read_b128 v[144:147], v204 offset:3072
	ds_read_b128 v[148:151], v204 offset:16384
	ds_read_b128 v[152:155], v204 offset:17408
	ds_read_b128 v[156:159], v204 offset:18432
	ds_read_b128 v[160:163], v204 offset:19456
	global_load_lds_dwordx4 v[224:225], off offset:128
	s_add_i32 m0, s51, 0xffffff80
	v_lshl_add_u64 v[194:195], s[8:9], 0, v[178:179]
	global_load_lds_dwordx4 v[226:227], off offset:128
	s_add_i32 m0, s42, 0xc000
	ds_read_b128 v[164:167], v205
	ds_read_b128 v[182:185], v205 offset:1024
	ds_read_b128 v[186:189], v205 offset:2048
	ds_read_b128 v[190:193], v205 offset:3072
	ds_read_b128 v[208:211], v205 offset:4096
	ds_read_b128 v[212:215], v205 offset:5120
	ds_read_b128 v[216:219], v205 offset:6144
	ds_read_b128 v[220:223], v205 offset:7168
	global_load_lds_dwordx4 v[194:195], off
	s_add_i32 m0, s42, 0xe000
	v_lshl_add_u64 v[194:195], s[8:9], 0, v[180:181]
	global_load_lds_dwordx4 v[194:195], off
	s_waitcnt vmcnt(8) lgkmcnt(0)
	s_barrier
	s_setprio 3
	v_mfma_f32_16x16x32_bf16 v[128:131], v[132:135], v[164:167], v[128:131]
	v_mfma_f32_16x16x32_bf16 v[124:127], v[140:143], v[164:167], v[124:127]
	v_mfma_f32_16x16x32_bf16 v[112:115], v[132:135], v[186:189], v[112:115]
	v_mfma_f32_16x16x32_bf16 v[108:111], v[140:143], v[186:189], v[108:111]
	v_mfma_f32_16x16x32_bf16 v[96:99], v[132:135], v[208:211], v[96:99]
	v_mfma_f32_16x16x32_bf16 v[92:95], v[140:143], v[208:211], v[92:95]
	v_mfma_f32_16x16x32_bf16 v[80:83], v[132:135], v[216:219], v[80:83]
	v_mfma_f32_16x16x32_bf16 v[76:79], v[140:143], v[216:219], v[76:79]
	v_mfma_f32_16x16x32_bf16 v[128:131], v[136:139], v[182:185], v[128:131]
	v_mfma_f32_16x16x32_bf16 v[124:127], v[144:147], v[182:185], v[124:127]
	v_mfma_f32_16x16x32_bf16 v[112:115], v[136:139], v[190:193], v[112:115]
	v_mfma_f32_16x16x32_bf16 v[108:111], v[144:147], v[190:193], v[108:111]
	v_mfma_f32_16x16x32_bf16 v[96:99], v[136:139], v[212:215], v[96:99]
	v_mfma_f32_16x16x32_bf16 v[92:95], v[144:147], v[212:215], v[92:95]
	v_mfma_f32_16x16x32_bf16 v[80:83], v[136:139], v[220:223], v[80:83]
	v_mfma_f32_16x16x32_bf16 v[76:79], v[144:147], v[220:223], v[76:79]
	s_setprio 0
	s_setprio 3
	v_mfma_f32_16x16x32_bf16 v[120:123], v[148:151], v[164:167], v[120:123]
	v_mfma_f32_16x16x32_bf16 v[116:119], v[156:159], v[164:167], v[116:119]
	v_mfma_f32_16x16x32_bf16 v[104:107], v[148:151], v[186:189], v[104:107]
	v_mfma_f32_16x16x32_bf16 v[100:103], v[156:159], v[186:189], v[100:103]
	v_mfma_f32_16x16x32_bf16 v[88:91], v[148:151], v[208:211], v[88:91]
	v_mfma_f32_16x16x32_bf16 v[84:87], v[156:159], v[208:211], v[84:87]
	v_mfma_f32_16x16x32_bf16 v[72:75], v[148:151], v[216:219], v[72:75]
	v_mfma_f32_16x16x32_bf16 v[68:71], v[156:159], v[216:219], v[68:71]
	v_mfma_f32_16x16x32_bf16 v[120:123], v[152:155], v[182:185], v[120:123]
	v_mfma_f32_16x16x32_bf16 v[116:119], v[160:163], v[182:185], v[116:119]
	v_mfma_f32_16x16x32_bf16 v[104:107], v[152:155], v[190:193], v[104:107]
	v_mfma_f32_16x16x32_bf16 v[100:103], v[160:163], v[190:193], v[100:103]
	v_mfma_f32_16x16x32_bf16 v[88:91], v[152:155], v[212:215], v[88:91]
	v_mfma_f32_16x16x32_bf16 v[84:87], v[160:163], v[212:215], v[84:87]
	v_mfma_f32_16x16x32_bf16 v[72:75], v[152:155], v[220:223], v[72:75]
	v_mfma_f32_16x16x32_bf16 v[68:71], v[160:163], v[220:223], v[68:71]
	s_setprio 0
	s_barrier
; #define PG8_STAGE(bufoff, gbase, voff) do { _Pragma("unroll") for (int _i = 0; _i < 2; ++_i) \
;         __builtin_amdgcn_global_load_lds((const unsigned*)((const char*)(gbase) + (voff)[_i]), (PG8_LAS unsigned*)(lds + (bufoff) + ldsw + _i * 8192), 16, 0, 0); } while (0)
; #define PG8_LDA(dst, b, h) do { _Pragma("unroll") for (int m = 0; m < 4; ++m) _Pragma("unroll") for (int k = 0; k < 2; ++k) dst[m][k] = *(const PG8_LAS bf16x8*)(lds + PG8_SA(b, h) + aoff + m * 2048 + k * 1024); } while (0)
; #define PG8_MMA(ai, bj, At, Bt) do { __builtin_amdgcn_s_setprio(1); _Pragma("unroll") for (int m = 0; m < 4; ++m) _Pragma("unroll") for (int n = 0; n < 2; ++n) _Pragma("unroll") for (int k = 0; k < 2; ++k) \
;         acc[ai][bj][m][n] = __builtin_amdgcn_mfma_f32_16x16x32_bf16(Bt[n][k], At[m][k], acc[ai][bj][m][n], 0, 0, 0); __builtin_amdgcn_s_setprio(0); } while (0)
; #define PG8_WAIT_V(n) asm volatile("s_waitcnt vmcnt(" #n ")" ::: "memory")
; #define PG8_WAIT_L(n) asm volatile("s_waitcnt lgkmcnt(" #n ")" ::: "memory")
; #define PG8_BAR __builtin_amdgcn_s_barrier()
; #define PG8_SCHED __builtin_amdgcn_sched_barrier(0)
; template <class Epi, class Sched, bool ALIGN_EPI = false, bool SP2 = false>
; __device__ __forceinline__ void gemm_phase(PG8_LAS unsigned char* lds, const Gemm g, const Sched& S, const Epi& E) {
;     ...
;             PG8_LDA(At, 0, 1); PG8_STAGE(PG8_SB(0, 0), b2, voffB); PG8_STAGE(PG8_SB(0, 1), b2 + hstep, voffB); PG8_STAGE(PG8_SA(0, 0), a2, voffA);
;             PG8_WAIT_V(8); PG8_WAIT_L(0); PG8_BAR; PG8_MMA(1, 0, At, B0); PG8_MMA(1, 1, At, B1); PG8_BAR; PG8_SCHED;
	v_lshl_add_u64 v[194:195], s[28:29], 0, v[168:169]
	s_add_i32 m0, s41, 0x10000
	ds_read_b128 v[164:167], v205 offset:16384
	ds_read_b128 v[182:185], v205 offset:17408
	ds_read_b128 v[186:189], v205 offset:18432
	ds_read_b128 v[190:193], v205 offset:19456
	ds_read_b128 v[208:211], v205 offset:20480
	ds_read_b128 v[212:215], v205 offset:21504
	ds_read_b128 v[216:219], v205 offset:22528
	ds_read_b128 v[220:223], v205 offset:23552
	global_load_lds_dwordx4 v[194:195], off
	s_add_i32 m0, s41, 0x12000
	s_add_u32 s54, s28, 0x40000
	v_lshl_add_u64 v[202:203], s[28:29], 0, v[172:173]
	s_addc_u32 s55, s29, 0
	global_load_lds_dwordx4 v[202:203], off
	v_lshl_add_u64 v[244:245], s[54:55], 0, v[168:169]
	s_add_i32 m0, s41, 0x14000
	v_lshl_add_u64 v[226:227], s[30:31], 0, v[170:171]
	global_load_lds_dwordx4 v[244:245], off
	s_add_i32 m0, s41, 0x16000
	v_lshl_add_u64 v[246:247], s[54:55], 0, v[172:173]
	global_load_lds_dwordx4 v[246:247], off
	v_lshl_add_u64 v[224:225], s[30:31], 0, v[0:1]
	s_waitcnt vmcnt(6) lgkmcnt(0)
	s_barrier
	s_setprio 3
	v_mfma_f32_16x16x32_bf16 v[64:67], v[132:135], v[164:167], v[64:67]
	v_mfma_f32_16x16x32_bf16 v[60:63], v[140:143], v[164:167], v[60:63]
	v_mfma_f32_16x16x32_bf16 v[48:51], v[132:135], v[186:189], v[48:51]
	v_mfma_f32_16x16x32_bf16 v[44:47], v[140:143], v[186:189], v[44:47]
	v_mfma_f32_16x16x32_bf16 v[32:35], v[132:135], v[208:211], v[32:35]
	v_mfma_f32_16x16x32_bf16 v[28:31], v[140:143], v[208:211], v[28:31]
	v_mfma_f32_16x16x32_bf16 v[16:19], v[132:135], v[216:219], v[16:19]
	v_mfma_f32_16x16x32_bf16 v[12:15], v[140:143], v[216:219], v[12:15]
	v_mfma_f32_16x16x32_bf16 v[64:67], v[136:139], v[182:185], v[64:67]
	v_mfma_f32_16x16x32_bf16 v[60:63], v[144:147], v[182:185], v[60:63]
	v_mfma_f32_16x16x32_bf16 v[48:51], v[136:139], v[190:193], v[48:51]
	v_mfma_f32_16x16x32_bf16 v[44:47], v[144:147], v[190:193], v[44:47]
	v_mfma_f32_16x16x32_bf16 v[32:35], v[136:139], v[212:215], v[32:35]
	v_mfma_f32_16x16x32_bf16 v[28:31], v[144:147], v[212:215], v[28:31]
	v_mfma_f32_16x16x32_bf16 v[16:19], v[136:139], v[220:223], v[16:19]
	v_mfma_f32_16x16x32_bf16 v[12:15], v[144:147], v[220:223], v[12:15]
	s_setprio 0
	s_setprio 3
	v_mfma_f32_16x16x32_bf16 v[56:59], v[148:151], v[164:167], v[56:59]
	v_mfma_f32_16x16x32_bf16 v[52:55], v[156:159], v[164:167], v[52:55]
	v_mfma_f32_16x16x32_bf16 v[40:43], v[148:151], v[186:189], v[40:43]
	v_mfma_f32_16x16x32_bf16 v[36:39], v[156:159], v[186:189], v[36:39]
	v_mfma_f32_16x16x32_bf16 v[24:27], v[148:151], v[208:211], v[24:27]
	v_mfma_f32_16x16x32_bf16 v[20:23], v[156:159], v[208:211], v[20:23]
	v_mfma_f32_16x16x32_bf16 v[8:11], v[148:151], v[216:219], v[8:11]
	v_mfma_f32_16x16x32_bf16 v[4:7], v[156:159], v[216:219], v[4:7]
	v_mfma_f32_16x16x32_bf16 v[56:59], v[152:155], v[182:185], v[56:59]
	v_mfma_f32_16x16x32_bf16 v[52:55], v[160:163], v[182:185], v[52:55]
	v_mfma_f32_16x16x32_bf16 v[40:43], v[152:155], v[190:193], v[40:43]
	v_mfma_f32_16x16x32_bf16 v[36:39], v[160:163], v[190:193], v[36:39]
	v_mfma_f32_16x16x32_bf16 v[24:27], v[152:155], v[212:215], v[24:27]
	v_mfma_f32_16x16x32_bf16 v[20:23], v[160:163], v[212:215], v[20:23]
	v_mfma_f32_16x16x32_bf16 v[8:11], v[152:155], v[220:223], v[8:11]
	v_mfma_f32_16x16x32_bf16 v[4:7], v[160:163], v[220:223], v[4:7]
	s_setprio 0
	s_barrier
; #define PG8_STAGE(bufoff, gbase, voff) do { _Pragma("unroll") for (int _i = 0; _i < 2; ++_i) \
;         __builtin_amdgcn_global_load_lds((const unsigned*)((const char*)(gbase) + (voff)[_i]), (PG8_LAS unsigned*)(lds + (bufoff) + ldsw + _i * 8192), 16, 0, 0); } while (0)
; #define PG8_LDA(dst, b, h) do { _Pragma("unroll") for (int m = 0; m < 4; ++m) _Pragma("unroll") for (int k = 0; k < 2; ++k) dst[m][k] = *(const PG8_LAS bf16x8*)(lds + PG8_SA(b, h) + aoff + m * 2048 + k * 1024); } while (0)
; #define PG8_LDB(dst, b, h) do { _Pragma("unroll") for (int n = 0; n < 2; ++n) _Pragma("unroll") for (int k = 0; k < 2; ++k) dst[n][k] = *(const PG8_LAS bf16x8*)(lds + PG8_SB(b, h) + boff + n * 2048 + k * 1024); } while (0)
; #define PG8_MMA(ai, bj, At, Bt) do { __builtin_amdgcn_s_setprio(1); _Pragma("unroll") for (int m = 0; m < 4; ++m) _Pragma("unroll") for (int n = 0; n < 2; ++n) _Pragma("unroll") for (int k = 0; k < 2; ++k) \
;         acc[ai][bj][m][n] = __builtin_amdgcn_mfma_f32_16x16x32_bf16(Bt[n][k], At[m][k], acc[ai][bj][m][n], 0, 0, 0); __builtin_amdgcn_s_setprio(0); } while (0)
; #define PG8_WAIT_V(n) asm volatile("s_waitcnt vmcnt(" #n ")" ::: "memory")
; #define PG8_WAIT_L(n) asm volatile("s_waitcnt lgkmcnt(" #n ")" ::: "memory")
; #define PG8_BAR __builtin_amdgcn_s_barrier()
; #define PG8_SCHED __builtin_amdgcn_sched_barrier(0)
; template <class Epi, class Sched, bool ALIGN_EPI = false, bool SP2 = false>
; __device__ __forceinline__ void gemm_phase(PG8_LAS unsigned char* lds, const Gemm g, const Sched& S, const Epi& E) {
;     ...
;             PG8_LDB(B0, 1, 0); PG8_LDB(B1, 1, 1); PG8_SCHED; PG8_LDA(At, 1, 0); PG8_STAGE(PG8_SA(0, 1), a2 + hstep, voffA);
;             PG8_WAIT_V(8); PG8_WAIT_L(0); PG8_BAR; PG8_MMA(0, 0, At, B0); PG8_MMA(0, 1, At, B1); PG8_BAR; PG8_SCHED;
;             PG8_LDA(At, 1, 1); PG8_STAGE(PG8_SB(1, 0), b3, voffB); PG8_STAGE(PG8_SB(1, 1), b3 + hstep, voffB); PG8_STAGE(PG8_SA(1, 0), a3, voffA);
;             PG8_WAIT_V(8); PG8_WAIT_L(0); PG8_BAR; PG8_MMA(1, 0, At, B0); PG8_MMA(1, 1, At, B1); PG8_BAR; PG8_SCHED;
.Lkmid_0:
	ds_read_b128 v[132:135], v204 offset:32768
	ds_read_b128 v[136:139], v204 offset:33792
	ds_read_b128 v[140:143], v204 offset:34816
	ds_read_b128 v[144:147], v204 offset:35840
	ds_read_b128 v[148:151], v204 offset:49152
	ds_read_b128 v[152:155], v204 offset:50176
	ds_read_b128 v[156:159], v204 offset:51200
	ds_read_b128 v[160:163], v204 offset:52224
	s_mov_b32 m0, s42
	s_add_u32 s30, s30, 0x40000
	s_addc_u32 s31, s31, 0
	global_load_lds_dwordx4 v[224:225], off
	s_mov_b32 m0, s43
	v_lshl_add_u64 v[228:229], s[30:31], 0, v[0:1]
	global_load_lds_dwordx4 v[226:227], off
	s_mov_b32 m0, s46
	ds_read_b128 v[164:167], v205 offset:32768
	ds_read_b128 v[182:185], v205 offset:33792
	ds_read_b128 v[186:189], v205 offset:34816
	ds_read_b128 v[190:193], v205 offset:35840
	ds_read_b128 v[208:211], v205 offset:36864
	ds_read_b128 v[212:215], v205 offset:37888
	ds_read_b128 v[216:219], v205 offset:38912
	ds_read_b128 v[220:223], v205 offset:39936
	global_load_lds_dwordx4 v[228:229], off
	s_mov_b32 m0, s47
	v_lshl_add_u64 v[228:229], s[30:31], 0, v[170:171]
	global_load_lds_dwordx4 v[228:229], off
	s_waitcnt vmcnt(8) lgkmcnt(0)
	s_barrier
	s_setprio 3
	v_mfma_f32_16x16x32_bf16 v[128:131], v[132:135], v[164:167], v[128:131]
	v_mfma_f32_16x16x32_bf16 v[124:127], v[140:143], v[164:167], v[124:127]
	v_mfma_f32_16x16x32_bf16 v[112:115], v[132:135], v[186:189], v[112:115]
	v_mfma_f32_16x16x32_bf16 v[108:111], v[140:143], v[186:189], v[108:111]
	v_mfma_f32_16x16x32_bf16 v[96:99], v[132:135], v[208:211], v[96:99]
	v_mfma_f32_16x16x32_bf16 v[92:95], v[140:143], v[208:211], v[92:95]
	v_mfma_f32_16x16x32_bf16 v[80:83], v[132:135], v[216:219], v[80:83]
	v_mfma_f32_16x16x32_bf16 v[76:79], v[140:143], v[216:219], v[76:79]
	v_mfma_f32_16x16x32_bf16 v[128:131], v[136:139], v[182:185], v[128:131]
	v_mfma_f32_16x16x32_bf16 v[124:127], v[144:147], v[182:185], v[124:127]
	v_mfma_f32_16x16x32_bf16 v[112:115], v[136:139], v[190:193], v[112:115]
	v_mfma_f32_16x16x32_bf16 v[108:111], v[144:147], v[190:193], v[108:111]
	v_mfma_f32_16x16x32_bf16 v[96:99], v[136:139], v[212:215], v[96:99]
	v_mfma_f32_16x16x32_bf16 v[92:95], v[144:147], v[212:215], v[92:95]
	v_mfma_f32_16x16x32_bf16 v[80:83], v[136:139], v[220:223], v[80:83]
	v_mfma_f32_16x16x32_bf16 v[76:79], v[144:147], v[220:223], v[76:79]
	s_setprio 0
	s_setprio 3
	v_mfma_f32_16x16x32_bf16 v[120:123], v[148:151], v[164:167], v[120:123]
	v_mfma_f32_16x16x32_bf16 v[116:119], v[156:159], v[164:167], v[116:119]
	v_mfma_f32_16x16x32_bf16 v[104:107], v[148:151], v[186:189], v[104:107]
	v_mfma_f32_16x16x32_bf16 v[100:103], v[156:159], v[186:189], v[100:103]
	v_mfma_f32_16x16x32_bf16 v[88:91], v[148:151], v[208:211], v[88:91]
	v_mfma_f32_16x16x32_bf16 v[84:87], v[156:159], v[208:211], v[84:87]
	v_mfma_f32_16x16x32_bf16 v[72:75], v[148:151], v[216:219], v[72:75]
	v_mfma_f32_16x16x32_bf16 v[68:71], v[156:159], v[216:219], v[68:71]
	v_mfma_f32_16x16x32_bf16 v[120:123], v[152:155], v[182:185], v[120:123]
	v_mfma_f32_16x16x32_bf16 v[116:119], v[160:163], v[182:185], v[116:119]
	v_mfma_f32_16x16x32_bf16 v[104:107], v[152:155], v[190:193], v[104:107]
	v_mfma_f32_16x16x32_bf16 v[100:103], v[160:163], v[190:193], v[100:103]
	v_mfma_f32_16x16x32_bf16 v[88:91], v[152:155], v[212:215], v[88:91]
	v_mfma_f32_16x16x32_bf16 v[84:87], v[160:163], v[212:215], v[84:87]
	v_mfma_f32_16x16x32_bf16 v[72:75], v[152:155], v[220:223], v[72:75]
	v_mfma_f32_16x16x32_bf16 v[68:71], v[160:163], v[220:223], v[68:71]
	s_setprio 0
	s_barrier
	s_add_i32 m0, s41, 0x17f80
	ds_read_b128 v[164:167], v205 offset:49152
	ds_read_b128 v[182:185], v205 offset:50176
	ds_read_b128 v[186:189], v205 offset:51200
	ds_read_b128 v[190:193], v205 offset:52224
	ds_read_b128 v[208:211], v205 offset:53248
	ds_read_b128 v[212:215], v205 offset:54272
	ds_read_b128 v[216:219], v205 offset:55296
	ds_read_b128 v[220:223], v205 offset:56320
	global_load_lds_dwordx4 v[194:195], off offset:128
	s_add_i32 m0, s41, 0x19f80
	s_add_u32 s8, s8, 0x100
	s_addc_u32 s9, s9, 0
	global_load_lds_dwordx4 v[202:203], off offset:128
	s_add_i32 m0, s41, 0x1bf80
	s_add_u32 s23, s23, 0x100
	s_addc_u32 s44, s44, 0
	global_load_lds_dwordx4 v[244:245], off offset:128
	s_add_i32 m0, s41, 0x1df80
	s_cmp_eq_u32 s45, 12
	global_load_lds_dwordx4 v[246:247], off offset:128
	s_cbranch_scc0 .Lks4_0
	s_add_i32 m0, s50, 0xffffff80
	s_nop 0
	global_load_lds_dwordx4 v[224:225], off offset:128
	s_add_i32 m0, s51, 0xffffff80
	s_nop 0
	global_load_lds_dwordx4 v[226:227], off offset:128
.Lks4_0:
	s_waitcnt vmcnt(6) lgkmcnt(0)
	s_barrier
	s_setprio 3
	v_mfma_f32_16x16x32_bf16 v[64:67], v[132:135], v[164:167], v[64:67]
	v_mfma_f32_16x16x32_bf16 v[60:63], v[140:143], v[164:167], v[60:63]
	v_mfma_f32_16x16x32_bf16 v[48:51], v[132:135], v[186:189], v[48:51]
	v_mfma_f32_16x16x32_bf16 v[44:47], v[140:143], v[186:189], v[44:47]
	v_mfma_f32_16x16x32_bf16 v[32:35], v[132:135], v[208:211], v[32:35]
	v_mfma_f32_16x16x32_bf16 v[28:31], v[140:143], v[208:211], v[28:31]
	v_mfma_f32_16x16x32_bf16 v[16:19], v[132:135], v[216:219], v[16:19]
	v_mfma_f32_16x16x32_bf16 v[12:15], v[140:143], v[216:219], v[12:15]
	v_mfma_f32_16x16x32_bf16 v[64:67], v[136:139], v[182:185], v[64:67]
	v_mfma_f32_16x16x32_bf16 v[60:63], v[144:147], v[182:185], v[60:63]
	v_mfma_f32_16x16x32_bf16 v[48:51], v[136:139], v[190:193], v[48:51]
	v_mfma_f32_16x16x32_bf16 v[44:47], v[144:147], v[190:193], v[44:47]
	v_mfma_f32_16x16x32_bf16 v[32:35], v[136:139], v[212:215], v[32:35]
	v_mfma_f32_16x16x32_bf16 v[28:31], v[144:147], v[212:215], v[28:31]
	v_mfma_f32_16x16x32_bf16 v[16:19], v[136:139], v[220:223], v[16:19]
	v_mfma_f32_16x16x32_bf16 v[12:15], v[144:147], v[220:223], v[12:15]
	s_setprio 0
	s_setprio 3
	v_mfma_f32_16x16x32_bf16 v[56:59], v[148:151], v[164:167], v[56:59]
	v_mfma_f32_16x16x32_bf16 v[52:55], v[156:159], v[164:167], v[52:55]
	v_mfma_f32_16x16x32_bf16 v[40:43], v[148:151], v[186:189], v[40:43]
	v_mfma_f32_16x16x32_bf16 v[36:39], v[156:159], v[186:189], v[36:39]
	v_mfma_f32_16x16x32_bf16 v[24:27], v[148:151], v[208:211], v[24:27]
	v_mfma_f32_16x16x32_bf16 v[20:23], v[156:159], v[208:211], v[20:23]
	v_mfma_f32_16x16x32_bf16 v[8:11], v[148:151], v[216:219], v[8:11]
	v_mfma_f32_16x16x32_bf16 v[4:7], v[156:159], v[216:219], v[4:7]
	v_mfma_f32_16x16x32_bf16 v[56:59], v[152:155], v[182:185], v[56:59]
	v_mfma_f32_16x16x32_bf16 v[52:55], v[160:163], v[182:185], v[52:55]
	v_mfma_f32_16x16x32_bf16 v[40:43], v[152:155], v[190:193], v[40:43]
	v_mfma_f32_16x16x32_bf16 v[36:39], v[160:163], v[190:193], v[36:39]
	v_mfma_f32_16x16x32_bf16 v[24:27], v[152:155], v[212:215], v[24:27]
	v_mfma_f32_16x16x32_bf16 v[20:23], v[160:163], v[212:215], v[20:23]
	v_mfma_f32_16x16x32_bf16 v[8:11], v[152:155], v[220:223], v[8:11]
	v_mfma_f32_16x16x32_bf16 v[4:7], v[160:163], v[220:223], v[4:7]
	s_setprio 0
	s_barrier
	s_add_i32 s45, s45, 2
	s_cmp_gt_u32 s45, 13
	s_cbranch_scc0 .LBB0_100
	s_and_b64 vcc, exec, s[14:15]
	s_cbranch_vccz .LBB0_103
	s_barrier

; #define PG8_STAGE(bufoff, gbase, voff) do { _Pragma("unroll") for (int _i = 0; _i < 2; ++_i) \
;         __builtin_amdgcn_global_load_lds((const unsigned*)((const char*)(gbase) + (voff)[_i]), (PG8_LAS unsigned*)(lds + (bufoff) + ldsw + _i * 8192), 16, 0, 0); } while (0)
; #define PG8_LDA(dst, b, h) do { _Pragma("unroll") for (int m = 0; m < 4; ++m) _Pragma("unroll") for (int k = 0; k < 2; ++k) dst[m][k] = *(const PG8_LAS bf16x8*)(lds + PG8_SA(b, h) + aoff + m * 2048 + k * 1024); } while (0)
; #define PG8_LDB(dst, b, h) do { _Pragma("unroll") for (int n = 0; n < 2; ++n) _Pragma("unroll") for (int k = 0; k < 2; ++k) dst[n][k] = *(const PG8_LAS bf16x8*)(lds + PG8_SB(b, h) + boff + n * 2048 + k * 1024); } while (0)
; #define PG8_WAIT_V(n) asm volatile("s_waitcnt vmcnt(" #n ")" ::: "memory")
; #define PG8_WAIT_L(n) asm volatile("s_waitcnt lgkmcnt(" #n ")" ::: "memory")
; #define PG8_BAR __builtin_amdgcn_s_barrier()
; #define PG8_SCHED __builtin_amdgcn_sched_barrier(0)
; template <class Epi, class Sched, bool ALIGN_EPI = false, bool SP2 = false>
; __device__ __forceinline__ void gemm_phase(PG8_LAS unsigned char* lds, const Gemm g, const Sched& S, const Epi& E) {
;     ...
;         const char* nA = has_next ? (const char*)g.A + (size_t)nxt.pm * tstep : cA; const char* nB = has_next ? (const char*)g.Bt + (size_t)nxt.pn * tstep : cB;
;         for (int t = 0; t < nt; t += 2) {
;             const bool last = (t == nt - 2);
;             const char* a1 = cA + (size_t)(t + 1) * kstep;
;             const char* a2 = last ? nA : cA + (size_t)(t + 2) * kstep; const char* b2 = last ? nB : cB + (size_t)(t + 2) * kstep;
;             const char* a3 = a2 + kstep; const char* b3 = b2 + kstep;
;             if (last && has_next) S.a_ready(nxt);
;             if constexpr (SP2) {
;             PG8_LDB(B0, 0, 0); PG8_LDB(B1, 0, 1); PG8_SCHED; PG8_LDA(At, 0, 0); PG8_STAGE(PG8_SA(1, 1), a1 + hstep, voffA);
;             PG8_WAIT_V(8); PG8_WAIT_L(0); PG8_BAR; PG8_MMA(0, 0, At, B0); PG8_MMA(0, 1, At, B1); PG8_BAR; PG8_SCHED;
;             PG8_LDA(At, 0, 1); PG8_STAGE(PG8_SB(0, 0), b2, voffB); PG8_STAGE(PG8_SB(0, 1), b2 + hstep, voffB); PG8_STAGE(PG8_SA(0, 0), a2, voffA);
;             PG8_WAIT_V(8); PG8_WAIT_L(0); PG8_BAR; PG8_MMA(1, 0, At, B0); PG8_MMA(1, 1, At, B1); PG8_BAR; PG8_SCHED;
.LBB0_328:
	s_ashr_i32 s17, s16, 31
	s_lshl_b64 s[20:21], s[16:17], 19
	s_add_u32 s20, s37, s20
	s_addc_u32 s21, s38, s21
	s_and_b64 s[22:23], s[6:7], exec
	s_cselect_b32 s3, s21, s29
	s_cselect_b32 s17, s20, s28
	s_ashr_i32 s19, s18, 31
	s_lshl_b64 s[22:23], s[18:19], 19
	s_add_u32 s22, s39, s22
	s_addc_u32 s23, s40, s23
	s_and_b64 s[34:35], s[6:7], exec
	s_cselect_b32 s19, s23, s31
	s_cselect_b32 s25, s22, s30
	s_add_u32 s28, s28, 0x40080
	s_addc_u32 s29, s29, 0
	s_add_u32 s27, s30, 0x100
	s_addc_u32 s44, s31, 0
	s_mov_b32 s45, -2
	s_add_u32 s30, s28, 0xfffc0080
	s_addc_u32 s31, s29, -1
	s_cmp_eq_u32 s45, 12
	s_cselect_b32 s35, s3, s31
	s_cselect_b32 s34, s17, s30
	s_cselect_b32 s31, s19, s44
	s_cselect_b32 s30, s25, s27
	ds_read_b128 v[108:111], v251
	ds_read_b128 v[112:115], v251 offset:1024
	ds_read_b128 v[124:127], v251 offset:2048
	ds_read_b128 v[128:131], v251 offset:3072
	ds_read_b128 v[132:135], v251 offset:16384
	ds_read_b128 v[140:143], v251 offset:17408
	ds_read_b128 v[148:151], v251 offset:18432
	ds_read_b128 v[156:159], v251 offset:19456
	v_lshl_add_u64 v[212:213], s[28:29], 0, v[208:209]
	s_add_i32 m0, s42, 0xc000
	ds_read_b128 v[164:167], v253
	ds_read_b128 v[168:171], v253 offset:1024
	ds_read_b128 v[172:175], v253 offset:2048
	ds_read_b128 v[176:179], v253 offset:3072
	ds_read_b128 v[180:183], v253 offset:4096
	ds_read_b128 v[184:187], v253 offset:5120
	ds_read_b128 v[188:191], v253 offset:6144
	ds_read_b128 v[192:195], v253 offset:7168
	global_load_lds_dwordx4 v[212:213], off
	s_add_i32 m0, s42, 0xe000
	v_lshl_add_u64 v[212:213], s[28:29], 0, v[210:211]
	global_load_lds_dwordx4 v[212:213], off
	s_waitcnt vmcnt(8) lgkmcnt(0)
	s_barrier
	s_setprio 3
	v_mfma_f32_16x16x32_bf16 v[160:163], v[108:111], v[164:167], 0
	v_mfma_f32_16x16x32_bf16 v[152:155], v[124:127], v[164:167], 0
	v_mfma_f32_16x16x32_bf16 v[120:123], v[108:111], v[172:175], 0
	v_mfma_f32_16x16x32_bf16 v[116:119], v[124:127], v[172:175], 0
	v_mfma_f32_16x16x32_bf16 v[96:99], v[108:111], v[180:183], 0
	v_mfma_f32_16x16x32_bf16 v[92:95], v[124:127], v[180:183], 0
	v_mfma_f32_16x16x32_bf16 v[80:83], v[108:111], v[188:191], 0
	v_mfma_f32_16x16x32_bf16 v[76:79], v[124:127], v[188:191], 0
	v_mfma_f32_16x16x32_bf16 v[160:163], v[112:115], v[168:171], v[160:163]
	v_mfma_f32_16x16x32_bf16 v[152:155], v[128:131], v[168:171], v[152:155]
	v_mfma_f32_16x16x32_bf16 v[120:123], v[112:115], v[176:179], v[120:123]
	v_mfma_f32_16x16x32_bf16 v[116:119], v[128:131], v[176:179], v[116:119]
	v_mfma_f32_16x16x32_bf16 v[96:99], v[112:115], v[184:187], v[96:99]
	v_mfma_f32_16x16x32_bf16 v[92:95], v[128:131], v[184:187], v[92:95]
	v_mfma_f32_16x16x32_bf16 v[80:83], v[112:115], v[192:195], v[80:83]
	v_mfma_f32_16x16x32_bf16 v[76:79], v[128:131], v[192:195], v[76:79]
	s_setprio 0
	s_setprio 3
	v_mfma_f32_16x16x32_bf16 v[144:147], v[132:135], v[164:167], 0
	v_mfma_f32_16x16x32_bf16 v[136:139], v[148:151], v[164:167], 0
	v_mfma_f32_16x16x32_bf16 v[104:107], v[132:135], v[172:175], 0
	v_mfma_f32_16x16x32_bf16 v[100:103], v[148:151], v[172:175], 0
	v_mfma_f32_16x16x32_bf16 v[88:91], v[132:135], v[180:183], 0
	v_mfma_f32_16x16x32_bf16 v[84:87], v[148:151], v[180:183], 0
	v_mfma_f32_16x16x32_bf16 v[72:75], v[132:135], v[188:191], 0
	v_mfma_f32_16x16x32_bf16 v[68:71], v[148:151], v[188:191], 0
	v_mfma_f32_16x16x32_bf16 v[144:147], v[140:143], v[168:171], v[144:147]
	v_mfma_f32_16x16x32_bf16 v[136:139], v[156:159], v[168:171], v[136:139]
	v_mfma_f32_16x16x32_bf16 v[104:107], v[140:143], v[176:179], v[104:107]
	v_mfma_f32_16x16x32_bf16 v[100:103], v[156:159], v[176:179], v[100:103]
	v_mfma_f32_16x16x32_bf16 v[88:91], v[140:143], v[184:187], v[88:91]
	v_mfma_f32_16x16x32_bf16 v[84:87], v[156:159], v[184:187], v[84:87]
	v_mfma_f32_16x16x32_bf16 v[72:75], v[140:143], v[192:195], v[72:75]
	v_mfma_f32_16x16x32_bf16 v[68:71], v[156:159], v[192:195], v[68:71]
	s_setprio 0
	s_barrier
	v_lshl_add_u64 v[212:213], s[30:31], 0, v[202:203]
	s_add_i32 m0, s41, 0x10000
	ds_read_b128 v[164:167], v253 offset:16384
	ds_read_b128 v[168:171], v253 offset:17408
	ds_read_b128 v[172:175], v253 offset:18432
	ds_read_b128 v[176:179], v253 offset:19456
	ds_read_b128 v[180:183], v253 offset:20480
	ds_read_b128 v[184:187], v253 offset:21504
	ds_read_b128 v[188:191], v253 offset:22528
	ds_read_b128 v[192:195], v253 offset:23552
	global_load_lds_dwordx4 v[212:213], off
	s_add_i32 m0, s41, 0x12000
	s_add_u32 s52, s30, 0x40000
	v_lshl_add_u64 v[214:215], s[30:31], 0, v[206:207]
	s_addc_u32 s53, s31, 0
	global_load_lds_dwordx4 v[214:215], off
	v_lshl_add_u64 v[244:245], s[52:53], 0, v[202:203]
	s_add_i32 m0, s41, 0x14000
	v_lshl_add_u64 v[218:219], s[34:35], 0, v[204:205]
	global_load_lds_dwordx4 v[244:245], off
	s_add_i32 m0, s41, 0x16000
	v_lshl_add_u64 v[246:247], s[52:53], 0, v[206:207]
	global_load_lds_dwordx4 v[246:247], off
	v_lshl_add_u64 v[216:217], s[34:35], 0, v[0:1]
	s_waitcnt vmcnt(6) lgkmcnt(0)
	s_barrier
; #define PG8_STAGE(bufoff, gbase, voff) do { _Pragma("unroll") for (int _i = 0; _i < 2; ++_i) \
;         __builtin_amdgcn_global_load_lds((const unsigned*)((const char*)(gbase) + (voff)[_i]), (PG8_LAS unsigned*)(lds + (bufoff) + ldsw + _i * 8192), 16, 0, 0); } while (0)
; #define PG8_LDA(dst, b, h) do { _Pragma("unroll") for (int m = 0; m < 4; ++m) _Pragma("unroll") for (int k = 0; k < 2; ++k) dst[m][k] = *(const PG8_LAS bf16x8*)(lds + PG8_SA(b, h) + aoff + m * 2048 + k * 1024); } while (0)
; #define PG8_LDB(dst, b, h) do { _Pragma("unroll") for (int n = 0; n < 2; ++n) _Pragma("unroll") for (int k = 0; k < 2; ++k) dst[n][k] = *(const PG8_LAS bf16x8*)(lds + PG8_SB(b, h) + boff + n * 2048 + k * 1024); } while (0)
; #define PG8_MMA(ai, bj, At, Bt) do { __builtin_amdgcn_s_setprio(1); _Pragma("unroll") for (int m = 0; m < 4; ++m) _Pragma("unroll") for (int n = 0; n < 2; ++n) _Pragma("unroll") for (int k = 0; k < 2; ++k) \
;         acc[ai][bj][m][n] = __builtin_amdgcn_mfma_f32_16x16x32_bf16(Bt[n][k], At[m][k], acc[ai][bj][m][n], 0, 0, 0); __builtin_amdgcn_s_setprio(0); } while (0)
; #define PG8_WAIT_V(n) asm volatile("s_waitcnt vmcnt(" #n ")" ::: "memory")
; #define PG8_WAIT_L(n) asm volatile("s_waitcnt lgkmcnt(" #n ")" ::: "memory")
; #define PG8_BAR __builtin_amdgcn_s_barrier()
; #define PG8_SCHED __builtin_amdgcn_sched_barrier(0)
; template <class Epi, class Sched, bool ALIGN_EPI = false, bool SP2 = false>
; __device__ __forceinline__ void gemm_phase(PG8_LAS unsigned char* lds, const Gemm g, const Sched& S, const Epi& E) {
;     ...
;             PG8_LDB(B0, 0, 0); PG8_LDB(B1, 0, 1); PG8_SCHED; PG8_LDA(At, 0, 0); PG8_STAGE(PG8_SA(1, 1), a1 + hstep, voffA);
;             PG8_WAIT_V(8); PG8_WAIT_L(0); PG8_BAR; PG8_MMA(0, 0, At, B0); PG8_MMA(0, 1, At, B1); PG8_BAR; PG8_SCHED;
;             PG8_LDA(At, 0, 1); PG8_STAGE(PG8_SB(0, 0), b2, voffB); PG8_STAGE(PG8_SB(0, 1), b2 + hstep, voffB); PG8_STAGE(PG8_SA(0, 0), a2, voffA);
;             PG8_WAIT_V(8); PG8_WAIT_L(0); PG8_BAR; PG8_MMA(1, 0, At, B0); PG8_MMA(1, 1, At, B1); PG8_BAR; PG8_SCHED;
	s_setprio 3
	v_mfma_f32_16x16x32_bf16 v[64:67], v[108:111], v[164:167], 0
	v_mfma_f32_16x16x32_bf16 v[60:63], v[124:127], v[164:167], 0
	v_mfma_f32_16x16x32_bf16 v[48:51], v[108:111], v[172:175], 0
	v_mfma_f32_16x16x32_bf16 v[44:47], v[124:127], v[172:175], 0
	v_mfma_f32_16x16x32_bf16 v[32:35], v[108:111], v[180:183], 0
	v_mfma_f32_16x16x32_bf16 v[28:31], v[124:127], v[180:183], 0
	v_mfma_f32_16x16x32_bf16 v[16:19], v[108:111], v[188:191], 0
	v_mfma_f32_16x16x32_bf16 v[12:15], v[124:127], v[188:191], 0
	v_mfma_f32_16x16x32_bf16 v[64:67], v[112:115], v[168:171], v[64:67]
	v_mfma_f32_16x16x32_bf16 v[60:63], v[128:131], v[168:171], v[60:63]
	v_mfma_f32_16x16x32_bf16 v[48:51], v[112:115], v[176:179], v[48:51]
	v_mfma_f32_16x16x32_bf16 v[44:47], v[128:131], v[176:179], v[44:47]
	v_mfma_f32_16x16x32_bf16 v[32:35], v[112:115], v[184:187], v[32:35]
	v_mfma_f32_16x16x32_bf16 v[28:31], v[128:131], v[184:187], v[28:31]
	v_mfma_f32_16x16x32_bf16 v[16:19], v[112:115], v[192:195], v[16:19]
	v_mfma_f32_16x16x32_bf16 v[12:15], v[128:131], v[192:195], v[12:15]
	s_setprio 0
	s_setprio 3
	v_mfma_f32_16x16x32_bf16 v[56:59], v[132:135], v[164:167], 0
	v_mfma_f32_16x16x32_bf16 v[52:55], v[148:151], v[164:167], 0
	v_mfma_f32_16x16x32_bf16 v[40:43], v[132:135], v[172:175], 0
	v_mfma_f32_16x16x32_bf16 v[36:39], v[148:151], v[172:175], 0
	v_mfma_f32_16x16x32_bf16 v[24:27], v[132:135], v[180:183], 0
	v_mfma_f32_16x16x32_bf16 v[20:23], v[148:151], v[180:183], 0
	v_mfma_f32_16x16x32_bf16 v[8:11], v[132:135], v[188:191], 0
	v_mfma_f32_16x16x32_bf16 v[4:7], v[148:151], v[188:191], 0
	v_mfma_f32_16x16x32_bf16 v[56:59], v[140:143], v[168:171], v[56:59]
	v_mfma_f32_16x16x32_bf16 v[52:55], v[156:159], v[168:171], v[52:55]
	v_mfma_f32_16x16x32_bf16 v[40:43], v[140:143], v[176:179], v[40:43]
	v_mfma_f32_16x16x32_bf16 v[36:39], v[156:159], v[176:179], v[36:39]
	v_mfma_f32_16x16x32_bf16 v[24:27], v[140:143], v[184:187], v[24:27]
	v_mfma_f32_16x16x32_bf16 v[20:23], v[156:159], v[184:187], v[20:23]
	v_mfma_f32_16x16x32_bf16 v[8:11], v[140:143], v[192:195], v[8:11]
	v_mfma_f32_16x16x32_bf16 v[4:7], v[156:159], v[192:195], v[4:7]
	s_setprio 0
	s_barrier
	s_branch .Lkmid_1
.LBB0_329:
	s_add_u32 s30, s28, 0xfffc0080
	s_addc_u32 s31, s29, -1
	s_cmp_eq_u32 s45, 12
	s_cselect_b32 s35, s3, s31
	s_cselect_b32 s34, s17, s30
	s_cselect_b32 s31, s19, s44
	s_cselect_b32 s30, s25, s27
	s_add_i32 m0, s49, 0xffffff80
	ds_read_b128 v[108:111], v251
	ds_read_b128 v[112:115], v251 offset:1024
	ds_read_b128 v[124:127], v251 offset:2048
	ds_read_b128 v[128:131], v251 offset:3072
	ds_read_b128 v[132:135], v251 offset:16384
	ds_read_b128 v[140:143], v251 offset:17408
	ds_read_b128 v[148:151], v251 offset:18432
	ds_read_b128 v[156:159], v251 offset:19456
	global_load_lds_dwordx4 v[216:217], off offset:128
	s_add_i32 m0, s50, 0xffffff80
	v_lshl_add_u64 v[212:213], s[28:29], 0, v[208:209]
	global_load_lds_dwordx4 v[218:219], off offset:128
	s_add_i32 m0, s42, 0xc000
	ds_read_b128 v[164:167], v253
	ds_read_b128 v[168:171], v253 offset:1024
	ds_read_b128 v[172:175], v253 offset:2048
	ds_read_b128 v[176:179], v253 offset:3072
	ds_read_b128 v[180:183], v253 offset:4096
	ds_read_b128 v[184:187], v253 offset:5120
	ds_read_b128 v[188:191], v253 offset:6144
	ds_read_b128 v[192:195], v253 offset:7168
	global_load_lds_dwordx4 v[212:213], off
	s_add_i32 m0, s42, 0xe000
	v_lshl_add_u64 v[212:213], s[28:29], 0, v[210:211]
	global_load_lds_dwordx4 v[212:213], off
	s_waitcnt vmcnt(8) lgkmcnt(0)
	s_barrier
	s_setprio 3
	v_mfma_f32_16x16x32_bf16 v[160:163], v[108:111], v[164:167], v[160:163]
	v_mfma_f32_16x16x32_bf16 v[152:155], v[124:127], v[164:167], v[152:155]
	v_mfma_f32_16x16x32_bf16 v[120:123], v[108:111], v[172:175], v[120:123]
	v_mfma_f32_16x16x32_bf16 v[116:119], v[124:127], v[172:175], v[116:119]
	v_mfma_f32_16x16x32_bf16 v[96:99], v[108:111], v[180:183], v[96:99]
	v_mfma_f32_16x16x32_bf16 v[92:95], v[124:127], v[180:183], v[92:95]
	v_mfma_f32_16x16x32_bf16 v[80:83], v[108:111], v[188:191], v[80:83]
	v_mfma_f32_16x16x32_bf16 v[76:79], v[124:127], v[188:191], v[76:79]
	v_mfma_f32_16x16x32_bf16 v[160:163], v[112:115], v[168:171], v[160:163]
	v_mfma_f32_16x16x32_bf16 v[152:155], v[128:131], v[168:171], v[152:155]
	v_mfma_f32_16x16x32_bf16 v[120:123], v[112:115], v[176:179], v[120:123]
	v_mfma_f32_16x16x32_bf16 v[116:119], v[128:131], v[176:179], v[116:119]
	v_mfma_f32_16x16x32_bf16 v[96:99], v[112:115], v[184:187], v[96:99]
	v_mfma_f32_16x16x32_bf16 v[92:95], v[128:131], v[184:187], v[92:95]
	v_mfma_f32_16x16x32_bf16 v[80:83], v[112:115], v[192:195], v[80:83]
	v_mfma_f32_16x16x32_bf16 v[76:79], v[128:131], v[192:195], v[76:79]
	s_setprio 0
	s_setprio 3
	v_mfma_f32_16x16x32_bf16 v[144:147], v[132:135], v[164:167], v[144:147]
	v_mfma_f32_16x16x32_bf16 v[136:139], v[148:151], v[164:167], v[136:139]
	v_mfma_f32_16x16x32_bf16 v[104:107], v[132:135], v[172:175], v[104:107]
	v_mfma_f32_16x16x32_bf16 v[100:103], v[148:151], v[172:175], v[100:103]
	v_mfma_f32_16x16x32_bf16 v[88:91], v[132:135], v[180:183], v[88:91]
	v_mfma_f32_16x16x32_bf16 v[84:87], v[148:151], v[180:183], v[84:87]
	v_mfma_f32_16x16x32_bf16 v[72:75], v[132:135], v[188:191], v[72:75]
	v_mfma_f32_16x16x32_bf16 v[68:71], v[148:151], v[188:191], v[68:71]
	v_mfma_f32_16x16x32_bf16 v[144:147], v[140:143], v[168:171], v[144:147]
	v_mfma_f32_16x16x32_bf16 v[136:139], v[156:159], v[168:171], v[136:139]
	v_mfma_f32_16x16x32_bf16 v[104:107], v[140:143], v[176:179], v[104:107]
	v_mfma_f32_16x16x32_bf16 v[100:103], v[156:159], v[176:179], v[100:103]
	v_mfma_f32_16x16x32_bf16 v[88:91], v[140:143], v[184:187], v[88:91]
	v_mfma_f32_16x16x32_bf16 v[84:87], v[156:159], v[184:187], v[84:87]
	v_mfma_f32_16x16x32_bf16 v[72:75], v[140:143], v[192:195], v[72:75]
	v_mfma_f32_16x16x32_bf16 v[68:71], v[156:159], v[192:195], v[68:71]
	s_setprio 0
	s_barrier
; #define PG8_STAGE(bufoff, gbase, voff) do { _Pragma("unroll") for (int _i = 0; _i < 2; ++_i) \
;         __builtin_amdgcn_global_load_lds((const unsigned*)((const char*)(gbase) + (voff)[_i]), (PG8_LAS unsigned*)(lds + (bufoff) + ldsw + _i * 8192), 16, 0, 0); } while (0)
; #define PG8_LDA(dst, b, h) do { _Pragma("unroll") for (int m = 0; m < 4; ++m) _Pragma("unroll") for (int k = 0; k < 2; ++k) dst[m][k] = *(const PG8_LAS bf16x8*)(lds + PG8_SA(b, h) + aoff + m * 2048 + k * 1024); } while (0)
; #define PG8_MMA(ai, bj, At, Bt) do { __builtin_amdgcn_s_setprio(1); _Pragma("unroll") for (int m = 0; m < 4; ++m) _Pragma("unroll") for (int n = 0; n < 2; ++n) _Pragma("unroll") for (int k = 0; k < 2; ++k) \
;         acc[ai][bj][m][n] = __builtin_amdgcn_mfma_f32_16x16x32_bf16(Bt[n][k], At[m][k], acc[ai][bj][m][n], 0, 0, 0); __builtin_amdgcn_s_setprio(0); } while (0)
; #define PG8_WAIT_V(n) asm volatile("s_waitcnt vmcnt(" #n ")" ::: "memory")
; #define PG8_WAIT_L(n) asm volatile("s_waitcnt lgkmcnt(" #n ")" ::: "memory")
; #define PG8_BAR __builtin_amdgcn_s_barrier()
; #define PG8_SCHED __builtin_amdgcn_sched_barrier(0)
; template <class Epi, class Sched, bool ALIGN_EPI = false, bool SP2 = false>
; __device__ __forceinline__ void gemm_phase(PG8_LAS unsigned char* lds, const Gemm g, const Sched& S, const Epi& E) {
;     ...
;             PG8_LDA(At, 0, 1); PG8_STAGE(PG8_SB(0, 0), b2, voffB); PG8_STAGE(PG8_SB(0, 1), b2 + hstep, voffB); PG8_STAGE(PG8_SA(0, 0), a2, voffA);
;             PG8_WAIT_V(8); PG8_WAIT_L(0); PG8_BAR; PG8_MMA(1, 0, At, B0); PG8_MMA(1, 1, At, B1); PG8_BAR; PG8_SCHED;
	v_lshl_add_u64 v[212:213], s[30:31], 0, v[202:203]
	s_add_i32 m0, s41, 0x10000
	ds_read_b128 v[164:167], v253 offset:16384
	ds_read_b128 v[168:171], v253 offset:17408
	ds_read_b128 v[172:175], v253 offset:18432
	ds_read_b128 v[176:179], v253 offset:19456
	ds_read_b128 v[180:183], v253 offset:20480
	ds_read_b128 v[184:187], v253 offset:21504
	ds_read_b128 v[188:191], v253 offset:22528
	ds_read_b128 v[192:195], v253 offset:23552
	global_load_lds_dwordx4 v[212:213], off
	s_add_i32 m0, s41, 0x12000
	s_add_u32 s52, s30, 0x40000
	v_lshl_add_u64 v[214:215], s[30:31], 0, v[206:207]
	s_addc_u32 s53, s31, 0
	global_load_lds_dwordx4 v[214:215], off
	v_lshl_add_u64 v[244:245], s[52:53], 0, v[202:203]
	s_add_i32 m0, s41, 0x14000
	v_lshl_add_u64 v[218:219], s[34:35], 0, v[204:205]
	global_load_lds_dwordx4 v[244:245], off
	s_add_i32 m0, s41, 0x16000
	v_lshl_add_u64 v[246:247], s[52:53], 0, v[206:207]
	global_load_lds_dwordx4 v[246:247], off
	v_lshl_add_u64 v[216:217], s[34:35], 0, v[0:1]
	s_waitcnt vmcnt(6) lgkmcnt(0)
	s_barrier
	s_setprio 3
	v_mfma_f32_16x16x32_bf16 v[64:67], v[108:111], v[164:167], v[64:67]
	v_mfma_f32_16x16x32_bf16 v[60:63], v[124:127], v[164:167], v[60:63]
	v_mfma_f32_16x16x32_bf16 v[48:51], v[108:111], v[172:175], v[48:51]
	v_mfma_f32_16x16x32_bf16 v[44:47], v[124:127], v[172:175], v[44:47]
	v_mfma_f32_16x16x32_bf16 v[32:35], v[108:111], v[180:183], v[32:35]
	v_mfma_f32_16x16x32_bf16 v[28:31], v[124:127], v[180:183], v[28:31]
	v_mfma_f32_16x16x32_bf16 v[16:19], v[108:111], v[188:191], v[16:19]
	v_mfma_f32_16x16x32_bf16 v[12:15], v[124:127], v[188:191], v[12:15]
	v_mfma_f32_16x16x32_bf16 v[64:67], v[112:115], v[168:171], v[64:67]
	v_mfma_f32_16x16x32_bf16 v[60:63], v[128:131], v[168:171], v[60:63]
	v_mfma_f32_16x16x32_bf16 v[48:51], v[112:115], v[176:179], v[48:51]
	v_mfma_f32_16x16x32_bf16 v[44:47], v[128:131], v[176:179], v[44:47]
	v_mfma_f32_16x16x32_bf16 v[32:35], v[112:115], v[184:187], v[32:35]
	v_mfma_f32_16x16x32_bf16 v[28:31], v[128:131], v[184:187], v[28:31]
	v_mfma_f32_16x16x32_bf16 v[16:19], v[112:115], v[192:195], v[16:19]
	v_mfma_f32_16x16x32_bf16 v[12:15], v[128:131], v[192:195], v[12:15]
	s_setprio 0
	s_setprio 3
	v_mfma_f32_16x16x32_bf16 v[56:59], v[132:135], v[164:167], v[56:59]
	v_mfma_f32_16x16x32_bf16 v[52:55], v[148:151], v[164:167], v[52:55]
	v_mfma_f32_16x16x32_bf16 v[40:43], v[132:135], v[172:175], v[40:43]
	v_mfma_f32_16x16x32_bf16 v[36:39], v[148:151], v[172:175], v[36:39]
	v_mfma_f32_16x16x32_bf16 v[24:27], v[132:135], v[180:183], v[24:27]
	v_mfma_f32_16x16x32_bf16 v[20:23], v[148:151], v[180:183], v[20:23]
	v_mfma_f32_16x16x32_bf16 v[8:11], v[132:135], v[188:191], v[8:11]
	v_mfma_f32_16x16x32_bf16 v[4:7], v[148:151], v[188:191], v[4:7]
	v_mfma_f32_16x16x32_bf16 v[56:59], v[140:143], v[168:171], v[56:59]
	v_mfma_f32_16x16x32_bf16 v[52:55], v[156:159], v[168:171], v[52:55]
	v_mfma_f32_16x16x32_bf16 v[40:43], v[140:143], v[176:179], v[40:43]
	v_mfma_f32_16x16x32_bf16 v[36:39], v[156:159], v[176:179], v[36:39]
	v_mfma_f32_16x16x32_bf16 v[24:27], v[140:143], v[184:187], v[24:27]
	v_mfma_f32_16x16x32_bf16 v[20:23], v[156:159], v[184:187], v[20:23]
	v_mfma_f32_16x16x32_bf16 v[8:11], v[140:143], v[192:195], v[8:11]
	v_mfma_f32_16x16x32_bf16 v[4:7], v[156:159], v[192:195], v[4:7]
	s_setprio 0
	s_barrier
; #define PG8_STAGE(bufoff, gbase, voff) do { _Pragma("unroll") for (int _i = 0; _i < 2; ++_i) \
;         __builtin_amdgcn_global_load_lds((const unsigned*)((const char*)(gbase) + (voff)[_i]), (PG8_LAS unsigned*)(lds + (bufoff) + ldsw + _i * 8192), 16, 0, 0); } while (0)
; #define PG8_LDA(dst, b, h) do { _Pragma("unroll") for (int m = 0; m < 4; ++m) _Pragma("unroll") for (int k = 0; k < 2; ++k) dst[m][k] = *(const PG8_LAS bf16x8*)(lds + PG8_SA(b, h) + aoff + m * 2048 + k * 1024); } while (0)
; #define PG8_LDB(dst, b, h) do { _Pragma("unroll") for (int n = 0; n < 2; ++n) _Pragma("unroll") for (int k = 0; k < 2; ++k) dst[n][k] = *(const PG8_LAS bf16x8*)(lds + PG8_SB(b, h) + boff + n * 2048 + k * 1024); } while (0)
; #define PG8_MMA(ai, bj, At, Bt) do { __builtin_amdgcn_s_setprio(1); _Pragma("unroll") for (int m = 0; m < 4; ++m) _Pragma("unroll") for (int n = 0; n < 2; ++n) _Pragma("unroll") for (int k = 0; k < 2; ++k) \
;         acc[ai][bj][m][n] = __builtin_amdgcn_mfma_f32_16x16x32_bf16(Bt[n][k], At[m][k], acc[ai][bj][m][n], 0, 0, 0); __builtin_amdgcn_s_setprio(0); } while (0)
; #define PG8_WAIT_V(n) asm volatile("s_waitcnt vmcnt(" #n ")" ::: "memory")
; #define PG8_WAIT_L(n) asm volatile("s_waitcnt lgkmcnt(" #n ")" ::: "memory")
; #define PG8_BAR __builtin_amdgcn_s_barrier()
; #define PG8_SCHED __builtin_amdgcn_sched_barrier(0)
; template <class Epi, class Sched, bool ALIGN_EPI = false, bool SP2 = false>
; __device__ __forceinline__ void gemm_phase(PG8_LAS unsigned char* lds, const Gemm g, const Sched& S, const Epi& E) {
;     ...
;             PG8_LDB(B0, 1, 0); PG8_LDB(B1, 1, 1); PG8_SCHED; PG8_LDA(At, 1, 0); PG8_STAGE(PG8_SA(0, 1), a2 + hstep, voffA);
;             PG8_WAIT_V(8); PG8_WAIT_L(0); PG8_BAR; PG8_MMA(0, 0, At, B0); PG8_MMA(0, 1, At, B1); PG8_BAR; PG8_SCHED;
;             PG8_LDA(At, 1, 1); PG8_STAGE(PG8_SB(1, 0), b3, voffB); PG8_STAGE(PG8_SB(1, 1), b3 + hstep, voffB); PG8_STAGE(PG8_SA(1, 0), a3, voffA);
;             PG8_WAIT_V(8); PG8_WAIT_L(0); PG8_BAR; PG8_MMA(1, 0, At, B0); PG8_MMA(1, 1, At, B1); PG8_BAR; PG8_SCHED;
.Lkmid_1:
	ds_read_b128 v[108:111], v251 offset:32768
	ds_read_b128 v[112:115], v251 offset:33792
	ds_read_b128 v[124:127], v251 offset:34816
	ds_read_b128 v[128:131], v251 offset:35840
	ds_read_b128 v[132:135], v251 offset:49152
	ds_read_b128 v[140:143], v251 offset:50176
	ds_read_b128 v[148:151], v251 offset:51200
	ds_read_b128 v[156:159], v251 offset:52224
	s_mov_b32 m0, s42
	s_add_u32 s34, s34, 0x40000
	s_addc_u32 s35, s35, 0
	global_load_lds_dwordx4 v[216:217], off
	s_mov_b32 m0, s43
	v_lshl_add_u64 v[220:221], s[34:35], 0, v[0:1]
	global_load_lds_dwordx4 v[218:219], off
	s_mov_b32 m0, s46
	ds_read_b128 v[164:167], v253 offset:32768
	ds_read_b128 v[168:171], v253 offset:33792
	ds_read_b128 v[172:175], v253 offset:34816
	ds_read_b128 v[176:179], v253 offset:35840
	ds_read_b128 v[180:183], v253 offset:36864
	ds_read_b128 v[184:187], v253 offset:37888
	ds_read_b128 v[188:191], v253 offset:38912
	ds_read_b128 v[192:195], v253 offset:39936
	global_load_lds_dwordx4 v[220:221], off
	s_mov_b32 m0, s47
	v_lshl_add_u64 v[220:221], s[34:35], 0, v[204:205]
	global_load_lds_dwordx4 v[220:221], off
	s_waitcnt vmcnt(8) lgkmcnt(0)
	s_barrier
	s_setprio 3
	v_mfma_f32_16x16x32_bf16 v[160:163], v[108:111], v[164:167], v[160:163]
	v_mfma_f32_16x16x32_bf16 v[152:155], v[124:127], v[164:167], v[152:155]
	v_mfma_f32_16x16x32_bf16 v[120:123], v[108:111], v[172:175], v[120:123]
	v_mfma_f32_16x16x32_bf16 v[116:119], v[124:127], v[172:175], v[116:119]
	v_mfma_f32_16x16x32_bf16 v[96:99], v[108:111], v[180:183], v[96:99]
	v_mfma_f32_16x16x32_bf16 v[92:95], v[124:127], v[180:183], v[92:95]
	v_mfma_f32_16x16x32_bf16 v[80:83], v[108:111], v[188:191], v[80:83]
	v_mfma_f32_16x16x32_bf16 v[76:79], v[124:127], v[188:191], v[76:79]
	v_mfma_f32_16x16x32_bf16 v[160:163], v[112:115], v[168:171], v[160:163]
	v_mfma_f32_16x16x32_bf16 v[152:155], v[128:131], v[168:171], v[152:155]
	v_mfma_f32_16x16x32_bf16 v[120:123], v[112:115], v[176:179], v[120:123]
	v_mfma_f32_16x16x32_bf16 v[116:119], v[128:131], v[176:179], v[116:119]
	v_mfma_f32_16x16x32_bf16 v[96:99], v[112:115], v[184:187], v[96:99]
	v_mfma_f32_16x16x32_bf16 v[92:95], v[128:131], v[184:187], v[92:95]
	v_mfma_f32_16x16x32_bf16 v[80:83], v[112:115], v[192:195], v[80:83]
	v_mfma_f32_16x16x32_bf16 v[76:79], v[128:131], v[192:195], v[76:79]
	s_setprio 0
	s_setprio 3
	v_mfma_f32_16x16x32_bf16 v[144:147], v[132:135], v[164:167], v[144:147]
	v_mfma_f32_16x16x32_bf16 v[136:139], v[148:151], v[164:167], v[136:139]
	v_mfma_f32_16x16x32_bf16 v[104:107], v[132:135], v[172:175], v[104:107]
	v_mfma_f32_16x16x32_bf16 v[100:103], v[148:151], v[172:175], v[100:103]
	v_mfma_f32_16x16x32_bf16 v[88:91], v[132:135], v[180:183], v[88:91]
	v_mfma_f32_16x16x32_bf16 v[84:87], v[148:151], v[180:183], v[84:87]
	v_mfma_f32_16x16x32_bf16 v[72:75], v[132:135], v[188:191], v[72:75]
	v_mfma_f32_16x16x32_bf16 v[68:71], v[148:151], v[188:191], v[68:71]
	v_mfma_f32_16x16x32_bf16 v[144:147], v[140:143], v[168:171], v[144:147]
	v_mfma_f32_16x16x32_bf16 v[136:139], v[156:159], v[168:171], v[136:139]
	v_mfma_f32_16x16x32_bf16 v[104:107], v[140:143], v[176:179], v[104:107]
	v_mfma_f32_16x16x32_bf16 v[100:103], v[156:159], v[176:179], v[100:103]
	v_mfma_f32_16x16x32_bf16 v[88:91], v[140:143], v[184:187], v[88:91]
	v_mfma_f32_16x16x32_bf16 v[84:87], v[156:159], v[184:187], v[84:87]
	v_mfma_f32_16x16x32_bf16 v[72:75], v[140:143], v[192:195], v[72:75]
	v_mfma_f32_16x16x32_bf16 v[68:71], v[156:159], v[192:195], v[68:71]
	s_setprio 0
	s_barrier
	s_add_i32 m0, s41, 0x17f80
	ds_read_b128 v[164:167], v253 offset:49152
	ds_read_b128 v[168:171], v253 offset:50176
	ds_read_b128 v[172:175], v253 offset:51200
	ds_read_b128 v[176:179], v253 offset:52224
	ds_read_b128 v[180:183], v253 offset:53248
	ds_read_b128 v[184:187], v253 offset:54272
	ds_read_b128 v[188:191], v253 offset:55296
	ds_read_b128 v[192:195], v253 offset:56320
	global_load_lds_dwordx4 v[212:213], off offset:128
	s_add_i32 m0, s41, 0x19f80
	s_add_u32 s28, s28, 0x100
	s_addc_u32 s29, s29, 0
	global_load_lds_dwordx4 v[214:215], off offset:128
	s_add_i32 m0, s41, 0x1bf80
	s_add_u32 s27, s27, 0x100
	s_addc_u32 s44, s44, 0
	global_load_lds_dwordx4 v[244:245], off offset:128
	s_add_i32 m0, s41, 0x1df80
	s_cmp_eq_u32 s45, 12
	global_load_lds_dwordx4 v[246:247], off offset:128
	s_cbranch_scc0 .Lks4_1
	s_add_i32 m0, s49, 0xffffff80
	s_nop 0
	global_load_lds_dwordx4 v[216:217], off offset:128
	s_add_i32 m0, s50, 0xffffff80
	s_nop 0
	global_load_lds_dwordx4 v[218:219], off offset:128
.Lks4_1:
	s_waitcnt vmcnt(6) lgkmcnt(0)
	s_barrier
	s_setprio 3
	v_mfma_f32_16x16x32_bf16 v[64:67], v[108:111], v[164:167], v[64:67]
	v_mfma_f32_16x16x32_bf16 v[60:63], v[124:127], v[164:167], v[60:63]
	v_mfma_f32_16x16x32_bf16 v[48:51], v[108:111], v[172:175], v[48:51]
	v_mfma_f32_16x16x32_bf16 v[44:47], v[124:127], v[172:175], v[44:47]
	v_mfma_f32_16x16x32_bf16 v[32:35], v[108:111], v[180:183], v[32:35]
	v_mfma_f32_16x16x32_bf16 v[28:31], v[124:127], v[180:183], v[28:31]
	v_mfma_f32_16x16x32_bf16 v[16:19], v[108:111], v[188:191], v[16:19]
	v_mfma_f32_16x16x32_bf16 v[12:15], v[124:127], v[188:191], v[12:15]
	v_mfma_f32_16x16x32_bf16 v[64:67], v[112:115], v[168:171], v[64:67]
	v_mfma_f32_16x16x32_bf16 v[60:63], v[128:131], v[168:171], v[60:63]
	v_mfma_f32_16x16x32_bf16 v[48:51], v[112:115], v[176:179], v[48:51]
	v_mfma_f32_16x16x32_bf16 v[44:47], v[128:131], v[176:179], v[44:47]
	v_mfma_f32_16x16x32_bf16 v[32:35], v[112:115], v[184:187], v[32:35]
	v_mfma_f32_16x16x32_bf16 v[28:31], v[128:131], v[184:187], v[28:31]
	v_mfma_f32_16x16x32_bf16 v[16:19], v[112:115], v[192:195], v[16:19]
	v_mfma_f32_16x16x32_bf16 v[12:15], v[128:131], v[192:195], v[12:15]
	s_setprio 0
	s_setprio 3
	v_mfma_f32_16x16x32_bf16 v[56:59], v[132:135], v[164:167], v[56:59]
	v_mfma_f32_16x16x32_bf16 v[52:55], v[148:151], v[164:167], v[52:55]
	v_mfma_f32_16x16x32_bf16 v[40:43], v[132:135], v[172:175], v[40:43]
	v_mfma_f32_16x16x32_bf16 v[36:39], v[148:151], v[172:175], v[36:39]
	v_mfma_f32_16x16x32_bf16 v[24:27], v[132:135], v[180:183], v[24:27]
	v_mfma_f32_16x16x32_bf16 v[20:23], v[148:151], v[180:183], v[20:23]
	v_mfma_f32_16x16x32_bf16 v[8:11], v[132:135], v[188:191], v[8:11]
	v_mfma_f32_16x16x32_bf16 v[4:7], v[148:151], v[188:191], v[4:7]
	v_mfma_f32_16x16x32_bf16 v[56:59], v[140:143], v[168:171], v[56:59]
	v_mfma_f32_16x16x32_bf16 v[52:55], v[156:159], v[168:171], v[52:55]
	v_mfma_f32_16x16x32_bf16 v[40:43], v[140:143], v[176:179], v[40:43]
	v_mfma_f32_16x16x32_bf16 v[36:39], v[156:159], v[176:179], v[36:39]
	v_mfma_f32_16x16x32_bf16 v[24:27], v[140:143], v[184:187], v[24:27]
	v_mfma_f32_16x16x32_bf16 v[20:23], v[156:159], v[184:187], v[20:23]
	v_mfma_f32_16x16x32_bf16 v[8:11], v[140:143], v[192:195], v[8:11]
	v_mfma_f32_16x16x32_bf16 v[4:7], v[156:159], v[192:195], v[4:7]
	s_setprio 0
	s_barrier
	s_add_i32 s45, s45, 2
	s_cmp_gt_u32 s45, 13
	s_cbranch_scc0 .LBB0_329
	s_and_b64 vcc, exec, s[14:15]
	s_cbranch_vccz .LBB0_332
	s_barrier

; #define PG8_STAGE(bufoff, gbase, voff) do { _Pragma("unroll") for (int _i = 0; _i < 2; ++_i) \
;         __builtin_amdgcn_global_load_lds((const unsigned*)((const char*)(gbase) + (voff)[_i]), (PG8_LAS unsigned*)(lds + (bufoff) + ldsw + _i * 8192), 16, 0, 0); } while (0)
; #define PG8_LDA(dst, b, h) do { _Pragma("unroll") for (int m = 0; m < 4; ++m) _Pragma("unroll") for (int k = 0; k < 2; ++k) dst[m][k] = *(const PG8_LAS bf16x8*)(lds + PG8_SA(b, h) + aoff + m * 2048 + k * 1024); } while (0)
; #define PG8_LDB(dst, b, h) do { _Pragma("unroll") for (int n = 0; n < 2; ++n) _Pragma("unroll") for (int k = 0; k < 2; ++k) dst[n][k] = *(const PG8_LAS bf16x8*)(lds + PG8_SB(b, h) + boff + n * 2048 + k * 1024); } while (0)
; #define PG8_WAIT_V(n) asm volatile("s_waitcnt vmcnt(" #n ")" ::: "memory")
; #define PG8_WAIT_L(n) asm volatile("s_waitcnt lgkmcnt(" #n ")" ::: "memory")
; #define PG8_BAR __builtin_amdgcn_s_barrier()
; #define PG8_SCHED __builtin_amdgcn_sched_barrier(0)
; template <class Epi, class Sched, bool ALIGN_EPI = false, bool SP2 = false>
; __device__ __forceinline__ void gemm_phase(PG8_LAS unsigned char* lds, const Gemm g, const Sched& S, const Epi& E) {
;     ...
;         const char* nA = has_next ? (const char*)g.A + (size_t)nxt.pm * tstep : cA; const char* nB = has_next ? (const char*)g.Bt + (size_t)nxt.pn * tstep : cB;
;         for (int t = 0; t < nt; t += 2) {
;             const bool last = (t == nt - 2);
;             const char* a1 = cA + (size_t)(t + 1) * kstep;
;             const char* a2 = last ? nA : cA + (size_t)(t + 2) * kstep; const char* b2 = last ? nB : cB + (size_t)(t + 2) * kstep;
;             const char* a3 = a2 + kstep; const char* b3 = b2 + kstep;
;             if (last && has_next) S.a_ready(nxt);
;             if constexpr (SP2) {
;             PG8_LDB(B0, 0, 0); PG8_LDB(B1, 0, 1); PG8_SCHED; PG8_LDA(At, 0, 0); PG8_STAGE(PG8_SA(1, 1), a1 + hstep, voffA);
;             PG8_WAIT_V(8); PG8_WAIT_L(0); PG8_BAR; PG8_MMA(0, 0, At, B0); PG8_MMA(0, 1, At, B1); PG8_BAR; PG8_SCHED;
;             PG8_LDA(At, 0, 1); PG8_STAGE(PG8_SB(0, 0), b2, voffB); PG8_STAGE(PG8_SB(0, 1), b2 + hstep, voffB); PG8_STAGE(PG8_SA(0, 0), a2, voffA);
;             PG8_WAIT_V(8); PG8_WAIT_L(0); PG8_BAR; PG8_MMA(1, 0, At, B0); PG8_MMA(1, 1, At, B1); PG8_BAR; PG8_SCHED;
.LBB0_404:
	s_ashr_i32 s17, s16, 31
	s_lshl_b64 s[20:21], s[16:17], 19
	s_add_u32 s20, s29, s20
	s_addc_u32 s21, s30, s21
	s_and_b64 s[22:23], s[4:5], exec
	s_cselect_b32 s7, s21, s9
	s_cselect_b32 s17, s20, s8
	s_ashr_i32 s19, s18, 31
	s_lshl_b64 s[22:23], s[18:19], 19
	s_add_u32 s22, s31, s22
	s_addc_u32 s23, s34, s23
	s_and_b64 s[26:27], s[4:5], exec
	s_cselect_b32 s19, s23, s25
	s_cselect_b32 s43, s22, s24
	s_add_u32 s8, s8, 0x40080
	s_addc_u32 s9, s9, 0
	s_add_u32 s44, s24, 0x100
	s_addc_u32 s45, s25, 0
	s_mov_b32 s46, -2
	s_add_u32 s24, s8, 0xfffc0080
	s_addc_u32 s25, s9, -1
	s_cmp_eq_u32 s46, 12
	s_cselect_b32 s27, s7, s25
	s_cselect_b32 s26, s17, s24
	s_cselect_b32 s25, s19, s45
	s_cselect_b32 s24, s43, s44
	s_add_i32 s50, 0, 0x14000
	ds_read_b128 v[144:147], v164
	ds_read_b128 v[148:151], v164 offset:1024
	ds_read_b128 v[152:155], v164 offset:2048
	ds_read_b128 v[156:159], v164 offset:3072
	ds_read_b128 v[160:163], v164 offset:16384
	ds_read_b128 v[168:171], v164 offset:17408
	ds_read_b128 v[172:175], v164 offset:18432
	ds_read_b128 v[176:179], v164 offset:19456
	v_lshl_add_u64 v[198:199], s[8:9], 0, v[140:141]
	s_add_i32 m0, s37, 0xc000
	ds_read_b128 v[180:183], v166
	ds_read_b128 v[184:187], v166 offset:1024
	ds_read_b128 v[188:191], v166 offset:2048
	ds_read_b128 v[192:195], v166 offset:3072
	ds_read_b128 v[202:205], v166 offset:4096
	ds_read_b128 v[206:209], v166 offset:5120
	ds_read_b128 v[210:213], v166 offset:6144
	ds_read_b128 v[214:217], v166 offset:7168
	global_load_lds_dwordx4 v[198:199], off
	s_add_i32 m0, s37, 0xe000
	v_lshl_add_u64 v[198:199], s[8:9], 0, v[142:143]
	global_load_lds_dwordx4 v[198:199], off
	s_waitcnt vmcnt(8) lgkmcnt(0)
	s_barrier
	s_setprio 3
	v_mfma_f32_16x16x32_bf16 v[128:131], v[144:147], v[180:183], 0
	v_mfma_f32_16x16x32_bf16 v[120:123], v[152:155], v[180:183], 0
	v_mfma_f32_16x16x32_bf16 v[112:115], v[144:147], v[188:191], 0
	v_mfma_f32_16x16x32_bf16 v[104:107], v[152:155], v[188:191], 0
	v_mfma_f32_16x16x32_bf16 v[96:99], v[144:147], v[202:205], 0
	v_mfma_f32_16x16x32_bf16 v[88:91], v[152:155], v[202:205], 0
	v_mfma_f32_16x16x32_bf16 v[80:83], v[144:147], v[210:213], 0
	v_mfma_f32_16x16x32_bf16 v[72:75], v[152:155], v[210:213], 0
	v_mfma_f32_16x16x32_bf16 v[128:131], v[148:151], v[184:187], v[128:131]
	v_mfma_f32_16x16x32_bf16 v[120:123], v[156:159], v[184:187], v[120:123]
	v_mfma_f32_16x16x32_bf16 v[112:115], v[148:151], v[192:195], v[112:115]
	v_mfma_f32_16x16x32_bf16 v[104:107], v[156:159], v[192:195], v[104:107]
	v_mfma_f32_16x16x32_bf16 v[96:99], v[148:151], v[206:209], v[96:99]
	v_mfma_f32_16x16x32_bf16 v[88:91], v[156:159], v[206:209], v[88:91]
	v_mfma_f32_16x16x32_bf16 v[80:83], v[148:151], v[214:217], v[80:83]
	v_mfma_f32_16x16x32_bf16 v[72:75], v[156:159], v[214:217], v[72:75]
	s_setprio 0
	s_setprio 3
	v_mfma_f32_16x16x32_bf16 v[124:127], v[160:163], v[180:183], 0
	v_mfma_f32_16x16x32_bf16 v[116:119], v[172:175], v[180:183], 0
	v_mfma_f32_16x16x32_bf16 v[108:111], v[160:163], v[188:191], 0
	v_mfma_f32_16x16x32_bf16 v[100:103], v[172:175], v[188:191], 0
	v_mfma_f32_16x16x32_bf16 v[92:95], v[160:163], v[202:205], 0
	v_mfma_f32_16x16x32_bf16 v[84:87], v[172:175], v[202:205], 0
	v_mfma_f32_16x16x32_bf16 v[76:79], v[160:163], v[210:213], 0
	v_mfma_f32_16x16x32_bf16 v[68:71], v[172:175], v[210:213], 0
	v_mfma_f32_16x16x32_bf16 v[124:127], v[168:171], v[184:187], v[124:127]
	v_mfma_f32_16x16x32_bf16 v[116:119], v[176:179], v[184:187], v[116:119]
	v_mfma_f32_16x16x32_bf16 v[108:111], v[168:171], v[192:195], v[108:111]
	v_mfma_f32_16x16x32_bf16 v[100:103], v[176:179], v[192:195], v[100:103]
	v_mfma_f32_16x16x32_bf16 v[92:95], v[168:171], v[206:209], v[92:95]
	v_mfma_f32_16x16x32_bf16 v[84:87], v[176:179], v[206:209], v[84:87]
	v_mfma_f32_16x16x32_bf16 v[76:79], v[168:171], v[214:217], v[76:79]
	v_mfma_f32_16x16x32_bf16 v[68:71], v[176:179], v[214:217], v[68:71]
	s_setprio 0
	s_barrier
	v_lshl_add_u64 v[198:199], s[24:25], 0, v[134:135]
	s_add_i32 m0, s35, 0x10000
	ds_read_b128 v[180:183], v166 offset:16384
	ds_read_b128 v[184:187], v166 offset:17408
	ds_read_b128 v[188:191], v166 offset:18432
	ds_read_b128 v[192:195], v166 offset:19456
	ds_read_b128 v[202:205], v166 offset:20480
	ds_read_b128 v[206:209], v166 offset:21504
	ds_read_b128 v[210:213], v166 offset:22528
	ds_read_b128 v[214:217], v166 offset:23552
	global_load_lds_dwordx4 v[198:199], off
	s_add_i32 m0, s35, 0x12000
	s_add_u32 s48, s24, 0x40000
	v_lshl_add_u64 v[218:219], s[24:25], 0, v[0:1]
	s_addc_u32 s49, s25, 0
	global_load_lds_dwordx4 v[218:219], off
	v_lshl_add_u64 v[244:245], s[48:49], 0, v[134:135]
	s_add_i32 m0, s35, 0x14000
	v_lshl_add_u64 v[222:223], s[26:27], 0, v[132:133]
	global_load_lds_dwordx4 v[244:245], off
	s_add_i32 m0, s35, 0x16000
	v_lshl_add_u64 v[246:247], s[48:49], 0, v[0:1]
	global_load_lds_dwordx4 v[246:247], off
	v_lshl_add_u64 v[220:221], s[26:27], 0, v[136:137]
	s_waitcnt vmcnt(6) lgkmcnt(0)
	s_barrier
; #define PG8_STAGE(bufoff, gbase, voff) do { _Pragma("unroll") for (int _i = 0; _i < 2; ++_i) \
;         __builtin_amdgcn_global_load_lds((const unsigned*)((const char*)(gbase) + (voff)[_i]), (PG8_LAS unsigned*)(lds + (bufoff) + ldsw + _i * 8192), 16, 0, 0); } while (0)
; #define PG8_LDA(dst, b, h) do { _Pragma("unroll") for (int m = 0; m < 4; ++m) _Pragma("unroll") for (int k = 0; k < 2; ++k) dst[m][k] = *(const PG8_LAS bf16x8*)(lds + PG8_SA(b, h) + aoff + m * 2048 + k * 1024); } while (0)
; #define PG8_LDB(dst, b, h) do { _Pragma("unroll") for (int n = 0; n < 2; ++n) _Pragma("unroll") for (int k = 0; k < 2; ++k) dst[n][k] = *(const PG8_LAS bf16x8*)(lds + PG8_SB(b, h) + boff + n * 2048 + k * 1024); } while (0)
; #define PG8_MMA(ai, bj, At, Bt) do { __builtin_amdgcn_s_setprio(1); _Pragma("unroll") for (int m = 0; m < 4; ++m) _Pragma("unroll") for (int n = 0; n < 2; ++n) _Pragma("unroll") for (int k = 0; k < 2; ++k) \
;         acc[ai][bj][m][n] = __builtin_amdgcn_mfma_f32_16x16x32_bf16(Bt[n][k], At[m][k], acc[ai][bj][m][n], 0, 0, 0); __builtin_amdgcn_s_setprio(0); } while (0)
; #define PG8_WAIT_V(n) asm volatile("s_waitcnt vmcnt(" #n ")" ::: "memory")
; #define PG8_WAIT_L(n) asm volatile("s_waitcnt lgkmcnt(" #n ")" ::: "memory")
; #define PG8_BAR __builtin_amdgcn_s_barrier()
; #define PG8_SCHED __builtin_amdgcn_sched_barrier(0)
; template <class Epi, class Sched, bool ALIGN_EPI = false, bool SP2 = false>
; __device__ __forceinline__ void gemm_phase(PG8_LAS unsigned char* lds, const Gemm g, const Sched& S, const Epi& E) {
;     ...
;             PG8_LDB(B0, 0, 0); PG8_LDB(B1, 0, 1); PG8_SCHED; PG8_LDA(At, 0, 0); PG8_STAGE(PG8_SA(1, 1), a1 + hstep, voffA);
;             PG8_WAIT_V(8); PG8_WAIT_L(0); PG8_BAR; PG8_MMA(0, 0, At, B0); PG8_MMA(0, 1, At, B1); PG8_BAR; PG8_SCHED;
;             PG8_LDA(At, 0, 1); PG8_STAGE(PG8_SB(0, 0), b2, voffB); PG8_STAGE(PG8_SB(0, 1), b2 + hstep, voffB); PG8_STAGE(PG8_SA(0, 0), a2, voffA);
;             PG8_WAIT_V(8); PG8_WAIT_L(0); PG8_BAR; PG8_MMA(1, 0, At, B0); PG8_MMA(1, 1, At, B1); PG8_BAR; PG8_SCHED;
	s_setprio 3
	v_mfma_f32_16x16x32_bf16 v[64:67], v[144:147], v[180:183], 0
	v_mfma_f32_16x16x32_bf16 v[56:59], v[152:155], v[180:183], 0
	v_mfma_f32_16x16x32_bf16 v[48:51], v[144:147], v[188:191], 0
	v_mfma_f32_16x16x32_bf16 v[40:43], v[152:155], v[188:191], 0
	v_mfma_f32_16x16x32_bf16 v[32:35], v[144:147], v[202:205], 0
	v_mfma_f32_16x16x32_bf16 v[24:27], v[152:155], v[202:205], 0
	v_mfma_f32_16x16x32_bf16 v[16:19], v[144:147], v[210:213], 0
	v_mfma_f32_16x16x32_bf16 v[8:11], v[152:155], v[210:213], 0
	v_mfma_f32_16x16x32_bf16 v[64:67], v[148:151], v[184:187], v[64:67]
	v_mfma_f32_16x16x32_bf16 v[56:59], v[156:159], v[184:187], v[56:59]
	v_mfma_f32_16x16x32_bf16 v[48:51], v[148:151], v[192:195], v[48:51]
	v_mfma_f32_16x16x32_bf16 v[40:43], v[156:159], v[192:195], v[40:43]
	v_mfma_f32_16x16x32_bf16 v[32:35], v[148:151], v[206:209], v[32:35]
	v_mfma_f32_16x16x32_bf16 v[24:27], v[156:159], v[206:209], v[24:27]
	v_mfma_f32_16x16x32_bf16 v[16:19], v[148:151], v[214:217], v[16:19]
	v_mfma_f32_16x16x32_bf16 v[8:11], v[156:159], v[214:217], v[8:11]
	s_setprio 0
	s_setprio 3
	v_mfma_f32_16x16x32_bf16 v[60:63], v[160:163], v[180:183], 0
	v_mfma_f32_16x16x32_bf16 v[52:55], v[172:175], v[180:183], 0
	v_mfma_f32_16x16x32_bf16 v[44:47], v[160:163], v[188:191], 0
	v_mfma_f32_16x16x32_bf16 v[36:39], v[172:175], v[188:191], 0
	v_mfma_f32_16x16x32_bf16 v[28:31], v[160:163], v[202:205], 0
	v_mfma_f32_16x16x32_bf16 v[20:23], v[172:175], v[202:205], 0
	v_mfma_f32_16x16x32_bf16 v[12:15], v[160:163], v[210:213], 0
	v_mfma_f32_16x16x32_bf16 v[4:7], v[172:175], v[210:213], 0
	v_mfma_f32_16x16x32_bf16 v[60:63], v[168:171], v[184:187], v[60:63]
	v_mfma_f32_16x16x32_bf16 v[52:55], v[176:179], v[184:187], v[52:55]
	v_mfma_f32_16x16x32_bf16 v[44:47], v[168:171], v[192:195], v[44:47]
	v_mfma_f32_16x16x32_bf16 v[36:39], v[176:179], v[192:195], v[36:39]
	v_mfma_f32_16x16x32_bf16 v[28:31], v[168:171], v[206:209], v[28:31]
	v_mfma_f32_16x16x32_bf16 v[20:23], v[176:179], v[206:209], v[20:23]
	v_mfma_f32_16x16x32_bf16 v[12:15], v[168:171], v[214:217], v[12:15]
	v_mfma_f32_16x16x32_bf16 v[4:7], v[176:179], v[214:217], v[4:7]
	s_setprio 0
	s_barrier
	s_branch .Lkmid_2
.LBB0_405:
	s_add_u32 s24, s8, 0xfffc0080
	s_addc_u32 s25, s9, -1
	s_cmp_eq_u32 s46, 12
	s_cselect_b32 s27, s7, s25
	s_cselect_b32 s26, s17, s24
	s_cselect_b32 s25, s19, s45
	s_cselect_b32 s24, s43, s44
	s_add_i32 m0, s41, 0xffffff80
	s_add_i32 s50, 0, 0x14000
	ds_read_b128 v[144:147], v164
	ds_read_b128 v[148:151], v164 offset:1024
	ds_read_b128 v[152:155], v164 offset:2048
	ds_read_b128 v[156:159], v164 offset:3072
	ds_read_b128 v[160:163], v164 offset:16384
	ds_read_b128 v[168:171], v164 offset:17408
	ds_read_b128 v[172:175], v164 offset:18432
	ds_read_b128 v[176:179], v164 offset:19456
	global_load_lds_dwordx4 v[220:221], off offset:128
	s_add_i32 m0, s42, 0xffffff80
	v_lshl_add_u64 v[198:199], s[8:9], 0, v[140:141]
	global_load_lds_dwordx4 v[222:223], off offset:128
	s_add_i32 m0, s37, 0xc000
	ds_read_b128 v[180:183], v166
	ds_read_b128 v[184:187], v166 offset:1024
	ds_read_b128 v[188:191], v166 offset:2048
	ds_read_b128 v[192:195], v166 offset:3072
	ds_read_b128 v[202:205], v166 offset:4096
	ds_read_b128 v[206:209], v166 offset:5120
	ds_read_b128 v[210:213], v166 offset:6144
	ds_read_b128 v[214:217], v166 offset:7168
	global_load_lds_dwordx4 v[198:199], off
	s_add_i32 m0, s37, 0xe000
	v_lshl_add_u64 v[198:199], s[8:9], 0, v[142:143]
	global_load_lds_dwordx4 v[198:199], off
	s_waitcnt vmcnt(8) lgkmcnt(0)
	s_barrier
	s_setprio 3
	v_mfma_f32_16x16x32_bf16 v[128:131], v[144:147], v[180:183], v[128:131]
	v_mfma_f32_16x16x32_bf16 v[120:123], v[152:155], v[180:183], v[120:123]
	v_mfma_f32_16x16x32_bf16 v[112:115], v[144:147], v[188:191], v[112:115]
	v_mfma_f32_16x16x32_bf16 v[104:107], v[152:155], v[188:191], v[104:107]
	v_mfma_f32_16x16x32_bf16 v[96:99], v[144:147], v[202:205], v[96:99]
	v_mfma_f32_16x16x32_bf16 v[88:91], v[152:155], v[202:205], v[88:91]
	v_mfma_f32_16x16x32_bf16 v[80:83], v[144:147], v[210:213], v[80:83]
	v_mfma_f32_16x16x32_bf16 v[72:75], v[152:155], v[210:213], v[72:75]
	v_mfma_f32_16x16x32_bf16 v[128:131], v[148:151], v[184:187], v[128:131]
	v_mfma_f32_16x16x32_bf16 v[120:123], v[156:159], v[184:187], v[120:123]
	v_mfma_f32_16x16x32_bf16 v[112:115], v[148:151], v[192:195], v[112:115]
	v_mfma_f32_16x16x32_bf16 v[104:107], v[156:159], v[192:195], v[104:107]
	v_mfma_f32_16x16x32_bf16 v[96:99], v[148:151], v[206:209], v[96:99]
	v_mfma_f32_16x16x32_bf16 v[88:91], v[156:159], v[206:209], v[88:91]
	v_mfma_f32_16x16x32_bf16 v[80:83], v[148:151], v[214:217], v[80:83]
	v_mfma_f32_16x16x32_bf16 v[72:75], v[156:159], v[214:217], v[72:75]
	s_setprio 0
	s_setprio 3
	v_mfma_f32_16x16x32_bf16 v[124:127], v[160:163], v[180:183], v[124:127]
	v_mfma_f32_16x16x32_bf16 v[116:119], v[172:175], v[180:183], v[116:119]
	v_mfma_f32_16x16x32_bf16 v[108:111], v[160:163], v[188:191], v[108:111]
	v_mfma_f32_16x16x32_bf16 v[100:103], v[172:175], v[188:191], v[100:103]
	v_mfma_f32_16x16x32_bf16 v[92:95], v[160:163], v[202:205], v[92:95]
	v_mfma_f32_16x16x32_bf16 v[84:87], v[172:175], v[202:205], v[84:87]
	v_mfma_f32_16x16x32_bf16 v[76:79], v[160:163], v[210:213], v[76:79]
	v_mfma_f32_16x16x32_bf16 v[68:71], v[172:175], v[210:213], v[68:71]
	v_mfma_f32_16x16x32_bf16 v[124:127], v[168:171], v[184:187], v[124:127]
	v_mfma_f32_16x16x32_bf16 v[116:119], v[176:179], v[184:187], v[116:119]
	v_mfma_f32_16x16x32_bf16 v[108:111], v[168:171], v[192:195], v[108:111]
	v_mfma_f32_16x16x32_bf16 v[100:103], v[176:179], v[192:195], v[100:103]
	v_mfma_f32_16x16x32_bf16 v[92:95], v[168:171], v[206:209], v[92:95]
	v_mfma_f32_16x16x32_bf16 v[84:87], v[176:179], v[206:209], v[84:87]
	v_mfma_f32_16x16x32_bf16 v[76:79], v[168:171], v[214:217], v[76:79]
	v_mfma_f32_16x16x32_bf16 v[68:71], v[176:179], v[214:217], v[68:71]
	s_setprio 0
	s_barrier
; #define PG8_STAGE(bufoff, gbase, voff) do { _Pragma("unroll") for (int _i = 0; _i < 2; ++_i) \
;         __builtin_amdgcn_global_load_lds((const unsigned*)((const char*)(gbase) + (voff)[_i]), (PG8_LAS unsigned*)(lds + (bufoff) + ldsw + _i * 8192), 16, 0, 0); } while (0)
; #define PG8_LDA(dst, b, h) do { _Pragma("unroll") for (int m = 0; m < 4; ++m) _Pragma("unroll") for (int k = 0; k < 2; ++k) dst[m][k] = *(const PG8_LAS bf16x8*)(lds + PG8_SA(b, h) + aoff + m * 2048 + k * 1024); } while (0)
; #define PG8_MMA(ai, bj, At, Bt) do { __builtin_amdgcn_s_setprio(1); _Pragma("unroll") for (int m = 0; m < 4; ++m) _Pragma("unroll") for (int n = 0; n < 2; ++n) _Pragma("unroll") for (int k = 0; k < 2; ++k) \
;         acc[ai][bj][m][n] = __builtin_amdgcn_mfma_f32_16x16x32_bf16(Bt[n][k], At[m][k], acc[ai][bj][m][n], 0, 0, 0); __builtin_amdgcn_s_setprio(0); } while (0)
; #define PG8_WAIT_V(n) asm volatile("s_waitcnt vmcnt(" #n ")" ::: "memory")
; #define PG8_WAIT_L(n) asm volatile("s_waitcnt lgkmcnt(" #n ")" ::: "memory")
; #define PG8_BAR __builtin_amdgcn_s_barrier()
; #define PG8_SCHED __builtin_amdgcn_sched_barrier(0)
; template <class Epi, class Sched, bool ALIGN_EPI = false, bool SP2 = false>
; __device__ __forceinline__ void gemm_phase(PG8_LAS unsigned char* lds, const Gemm g, const Sched& S, const Epi& E) {
;     ...
;             PG8_LDA(At, 0, 1); PG8_STAGE(PG8_SB(0, 0), b2, voffB); PG8_STAGE(PG8_SB(0, 1), b2 + hstep, voffB); PG8_STAGE(PG8_SA(0, 0), a2, voffA);
;             PG8_WAIT_V(8); PG8_WAIT_L(0); PG8_BAR; PG8_MMA(1, 0, At, B0); PG8_MMA(1, 1, At, B1); PG8_BAR; PG8_SCHED;
	v_lshl_add_u64 v[198:199], s[24:25], 0, v[134:135]
	s_add_i32 m0, s35, 0x10000
	ds_read_b128 v[180:183], v166 offset:16384
	ds_read_b128 v[184:187], v166 offset:17408
	ds_read_b128 v[188:191], v166 offset:18432
	ds_read_b128 v[192:195], v166 offset:19456
	ds_read_b128 v[202:205], v166 offset:20480
	ds_read_b128 v[206:209], v166 offset:21504
	ds_read_b128 v[210:213], v166 offset:22528
	ds_read_b128 v[214:217], v166 offset:23552
	global_load_lds_dwordx4 v[198:199], off
	s_add_i32 m0, s35, 0x12000
	s_add_u32 s48, s24, 0x40000
	v_lshl_add_u64 v[218:219], s[24:25], 0, v[0:1]
	s_addc_u32 s49, s25, 0
	global_load_lds_dwordx4 v[218:219], off
	v_lshl_add_u64 v[244:245], s[48:49], 0, v[134:135]
	s_add_i32 m0, s35, 0x14000
	v_lshl_add_u64 v[222:223], s[26:27], 0, v[132:133]
	global_load_lds_dwordx4 v[244:245], off
	s_add_i32 m0, s35, 0x16000
	v_lshl_add_u64 v[246:247], s[48:49], 0, v[0:1]
	global_load_lds_dwordx4 v[246:247], off
	v_lshl_add_u64 v[220:221], s[26:27], 0, v[136:137]
	s_waitcnt vmcnt(6) lgkmcnt(0)
	s_barrier
	s_setprio 3
	v_mfma_f32_16x16x32_bf16 v[64:67], v[144:147], v[180:183], v[64:67]
	v_mfma_f32_16x16x32_bf16 v[56:59], v[152:155], v[180:183], v[56:59]
	v_mfma_f32_16x16x32_bf16 v[48:51], v[144:147], v[188:191], v[48:51]
	v_mfma_f32_16x16x32_bf16 v[40:43], v[152:155], v[188:191], v[40:43]
	v_mfma_f32_16x16x32_bf16 v[32:35], v[144:147], v[202:205], v[32:35]
	v_mfma_f32_16x16x32_bf16 v[24:27], v[152:155], v[202:205], v[24:27]
	v_mfma_f32_16x16x32_bf16 v[16:19], v[144:147], v[210:213], v[16:19]
	v_mfma_f32_16x16x32_bf16 v[8:11], v[152:155], v[210:213], v[8:11]
	v_mfma_f32_16x16x32_bf16 v[64:67], v[148:151], v[184:187], v[64:67]
	v_mfma_f32_16x16x32_bf16 v[56:59], v[156:159], v[184:187], v[56:59]
	v_mfma_f32_16x16x32_bf16 v[48:51], v[148:151], v[192:195], v[48:51]
	v_mfma_f32_16x16x32_bf16 v[40:43], v[156:159], v[192:195], v[40:43]
	v_mfma_f32_16x16x32_bf16 v[32:35], v[148:151], v[206:209], v[32:35]
	v_mfma_f32_16x16x32_bf16 v[24:27], v[156:159], v[206:209], v[24:27]
	v_mfma_f32_16x16x32_bf16 v[16:19], v[148:151], v[214:217], v[16:19]
	v_mfma_f32_16x16x32_bf16 v[8:11], v[156:159], v[214:217], v[8:11]
	s_setprio 0
	s_setprio 3
	v_mfma_f32_16x16x32_bf16 v[60:63], v[160:163], v[180:183], v[60:63]
	v_mfma_f32_16x16x32_bf16 v[52:55], v[172:175], v[180:183], v[52:55]
	v_mfma_f32_16x16x32_bf16 v[44:47], v[160:163], v[188:191], v[44:47]
	v_mfma_f32_16x16x32_bf16 v[36:39], v[172:175], v[188:191], v[36:39]
	v_mfma_f32_16x16x32_bf16 v[28:31], v[160:163], v[202:205], v[28:31]
	v_mfma_f32_16x16x32_bf16 v[20:23], v[172:175], v[202:205], v[20:23]
	v_mfma_f32_16x16x32_bf16 v[12:15], v[160:163], v[210:213], v[12:15]
	v_mfma_f32_16x16x32_bf16 v[4:7], v[172:175], v[210:213], v[4:7]
	v_mfma_f32_16x16x32_bf16 v[60:63], v[168:171], v[184:187], v[60:63]
	v_mfma_f32_16x16x32_bf16 v[52:55], v[176:179], v[184:187], v[52:55]
	v_mfma_f32_16x16x32_bf16 v[44:47], v[168:171], v[192:195], v[44:47]
	v_mfma_f32_16x16x32_bf16 v[36:39], v[176:179], v[192:195], v[36:39]
	v_mfma_f32_16x16x32_bf16 v[28:31], v[168:171], v[206:209], v[28:31]
	v_mfma_f32_16x16x32_bf16 v[20:23], v[176:179], v[206:209], v[20:23]
	v_mfma_f32_16x16x32_bf16 v[12:15], v[168:171], v[214:217], v[12:15]
	v_mfma_f32_16x16x32_bf16 v[4:7], v[176:179], v[214:217], v[4:7]
	s_setprio 0
	s_barrier
; #define PG8_STAGE(bufoff, gbase, voff) do { _Pragma("unroll") for (int _i = 0; _i < 2; ++_i) \
;         __builtin_amdgcn_global_load_lds((const unsigned*)((const char*)(gbase) + (voff)[_i]), (PG8_LAS unsigned*)(lds + (bufoff) + ldsw + _i * 8192), 16, 0, 0); } while (0)
; #define PG8_LDA(dst, b, h) do { _Pragma("unroll") for (int m = 0; m < 4; ++m) _Pragma("unroll") for (int k = 0; k < 2; ++k) dst[m][k] = *(const PG8_LAS bf16x8*)(lds + PG8_SA(b, h) + aoff + m * 2048 + k * 1024); } while (0)
; #define PG8_LDB(dst, b, h) do { _Pragma("unroll") for (int n = 0; n < 2; ++n) _Pragma("unroll") for (int k = 0; k < 2; ++k) dst[n][k] = *(const PG8_LAS bf16x8*)(lds + PG8_SB(b, h) + boff + n * 2048 + k * 1024); } while (0)
; #define PG8_MMA(ai, bj, At, Bt) do { __builtin_amdgcn_s_setprio(1); _Pragma("unroll") for (int m = 0; m < 4; ++m) _Pragma("unroll") for (int n = 0; n < 2; ++n) _Pragma("unroll") for (int k = 0; k < 2; ++k) \
;         acc[ai][bj][m][n] = __builtin_amdgcn_mfma_f32_16x16x32_bf16(Bt[n][k], At[m][k], acc[ai][bj][m][n], 0, 0, 0); __builtin_amdgcn_s_setprio(0); } while (0)
; #define PG8_WAIT_V(n) asm volatile("s_waitcnt vmcnt(" #n ")" ::: "memory")
; #define PG8_WAIT_L(n) asm volatile("s_waitcnt lgkmcnt(" #n ")" ::: "memory")
; #define PG8_BAR __builtin_amdgcn_s_barrier()
; #define PG8_SCHED __builtin_amdgcn_sched_barrier(0)
; template <class Epi, class Sched, bool ALIGN_EPI = false, bool SP2 = false>
; __device__ __forceinline__ void gemm_phase(PG8_LAS unsigned char* lds, const Gemm g, const Sched& S, const Epi& E) {
;     ...
;             PG8_LDB(B0, 1, 0); PG8_LDB(B1, 1, 1); PG8_SCHED; PG8_LDA(At, 1, 0); PG8_STAGE(PG8_SA(0, 1), a2 + hstep, voffA);
;             PG8_WAIT_V(8); PG8_WAIT_L(0); PG8_BAR; PG8_MMA(0, 0, At, B0); PG8_MMA(0, 1, At, B1); PG8_BAR; PG8_SCHED;
;             PG8_LDA(At, 1, 1); PG8_STAGE(PG8_SB(1, 0), b3, voffB); PG8_STAGE(PG8_SB(1, 1), b3 + hstep, voffB); PG8_STAGE(PG8_SA(1, 0), a3, voffA);
;             PG8_WAIT_V(8); PG8_WAIT_L(0); PG8_BAR; PG8_MMA(1, 0, At, B0); PG8_MMA(1, 1, At, B1); PG8_BAR; PG8_SCHED;
.Lkmid_2:
	ds_read_b128 v[144:147], v164 offset:32768
	ds_read_b128 v[148:151], v164 offset:33792
	ds_read_b128 v[152:155], v164 offset:34816
	ds_read_b128 v[156:159], v164 offset:35840
	ds_read_b128 v[160:163], v164 offset:49152
	ds_read_b128 v[168:171], v164 offset:50176
	ds_read_b128 v[172:175], v164 offset:51200
	ds_read_b128 v[176:179], v164 offset:52224
	s_mov_b32 m0, s37
	s_add_u32 s26, s26, 0x40000
	s_addc_u32 s27, s27, 0
	global_load_lds_dwordx4 v[220:221], off
	s_mov_b32 m0, s38
	v_lshl_add_u64 v[224:225], s[26:27], 0, v[136:137]
	global_load_lds_dwordx4 v[222:223], off
	s_mov_b32 m0, s39
	ds_read_b128 v[180:183], v166 offset:32768
	ds_read_b128 v[184:187], v166 offset:33792
	ds_read_b128 v[188:191], v166 offset:34816
	ds_read_b128 v[192:195], v166 offset:35840
	ds_read_b128 v[202:205], v166 offset:36864
	ds_read_b128 v[206:209], v166 offset:37888
	ds_read_b128 v[210:213], v166 offset:38912
	ds_read_b128 v[214:217], v166 offset:39936
	global_load_lds_dwordx4 v[224:225], off
	s_mov_b32 m0, s40
	v_lshl_add_u64 v[224:225], s[26:27], 0, v[132:133]
	global_load_lds_dwordx4 v[224:225], off
	s_waitcnt vmcnt(8) lgkmcnt(0)
	s_barrier
	s_setprio 3
	v_mfma_f32_16x16x32_bf16 v[128:131], v[144:147], v[180:183], v[128:131]
	v_mfma_f32_16x16x32_bf16 v[120:123], v[152:155], v[180:183], v[120:123]
	v_mfma_f32_16x16x32_bf16 v[112:115], v[144:147], v[188:191], v[112:115]
	v_mfma_f32_16x16x32_bf16 v[104:107], v[152:155], v[188:191], v[104:107]
	v_mfma_f32_16x16x32_bf16 v[96:99], v[144:147], v[202:205], v[96:99]
	v_mfma_f32_16x16x32_bf16 v[88:91], v[152:155], v[202:205], v[88:91]
	v_mfma_f32_16x16x32_bf16 v[80:83], v[144:147], v[210:213], v[80:83]
	v_mfma_f32_16x16x32_bf16 v[72:75], v[152:155], v[210:213], v[72:75]
	v_mfma_f32_16x16x32_bf16 v[128:131], v[148:151], v[184:187], v[128:131]
	v_mfma_f32_16x16x32_bf16 v[120:123], v[156:159], v[184:187], v[120:123]
	v_mfma_f32_16x16x32_bf16 v[112:115], v[148:151], v[192:195], v[112:115]
	v_mfma_f32_16x16x32_bf16 v[104:107], v[156:159], v[192:195], v[104:107]
	v_mfma_f32_16x16x32_bf16 v[96:99], v[148:151], v[206:209], v[96:99]
	v_mfma_f32_16x16x32_bf16 v[88:91], v[156:159], v[206:209], v[88:91]
	v_mfma_f32_16x16x32_bf16 v[80:83], v[148:151], v[214:217], v[80:83]
	v_mfma_f32_16x16x32_bf16 v[72:75], v[156:159], v[214:217], v[72:75]
	s_setprio 0
	s_setprio 3
	v_mfma_f32_16x16x32_bf16 v[124:127], v[160:163], v[180:183], v[124:127]
	v_mfma_f32_16x16x32_bf16 v[116:119], v[172:175], v[180:183], v[116:119]
	v_mfma_f32_16x16x32_bf16 v[108:111], v[160:163], v[188:191], v[108:111]
	v_mfma_f32_16x16x32_bf16 v[100:103], v[172:175], v[188:191], v[100:103]
	v_mfma_f32_16x16x32_bf16 v[92:95], v[160:163], v[202:205], v[92:95]
	v_mfma_f32_16x16x32_bf16 v[84:87], v[172:175], v[202:205], v[84:87]
	v_mfma_f32_16x16x32_bf16 v[76:79], v[160:163], v[210:213], v[76:79]
	v_mfma_f32_16x16x32_bf16 v[68:71], v[172:175], v[210:213], v[68:71]
	v_mfma_f32_16x16x32_bf16 v[124:127], v[168:171], v[184:187], v[124:127]
	v_mfma_f32_16x16x32_bf16 v[116:119], v[176:179], v[184:187], v[116:119]
	v_mfma_f32_16x16x32_bf16 v[108:111], v[168:171], v[192:195], v[108:111]
	v_mfma_f32_16x16x32_bf16 v[100:103], v[176:179], v[192:195], v[100:103]
	v_mfma_f32_16x16x32_bf16 v[92:95], v[168:171], v[206:209], v[92:95]
	v_mfma_f32_16x16x32_bf16 v[84:87], v[176:179], v[206:209], v[84:87]
	v_mfma_f32_16x16x32_bf16 v[76:79], v[168:171], v[214:217], v[76:79]
	v_mfma_f32_16x16x32_bf16 v[68:71], v[176:179], v[214:217], v[68:71]
	s_setprio 0
	s_barrier
	s_add_i32 m0, s35, 0x17f80
	ds_read_b128 v[180:183], v166 offset:49152
	ds_read_b128 v[184:187], v166 offset:50176
	ds_read_b128 v[188:191], v166 offset:51200
	ds_read_b128 v[192:195], v166 offset:52224
	ds_read_b128 v[202:205], v166 offset:53248
	ds_read_b128 v[206:209], v166 offset:54272
	ds_read_b128 v[210:213], v166 offset:55296
	ds_read_b128 v[214:217], v166 offset:56320
	global_load_lds_dwordx4 v[198:199], off offset:128
	s_add_i32 m0, s35, 0x19f80
	s_add_u32 s8, s8, 0x100
	s_addc_u32 s9, s9, 0
	global_load_lds_dwordx4 v[218:219], off offset:128
	s_add_i32 m0, s35, 0x1bf80
	s_add_u32 s44, s44, 0x100
	s_addc_u32 s45, s45, 0
	global_load_lds_dwordx4 v[244:245], off offset:128
	s_add_i32 m0, s35, 0x1df80
	s_cmp_eq_u32 s46, 12
	global_load_lds_dwordx4 v[246:247], off offset:128
	s_cbranch_scc0 .Lks4_2
	s_add_i32 m0, s41, 0xffffff80
	s_nop 0
	global_load_lds_dwordx4 v[220:221], off offset:128
	s_add_i32 m0, s42, 0xffffff80
	s_nop 0
	global_load_lds_dwordx4 v[222:223], off offset:128
.Lks4_2:
	s_waitcnt vmcnt(6) lgkmcnt(0)
	s_barrier
	s_setprio 3
	v_mfma_f32_16x16x32_bf16 v[64:67], v[144:147], v[180:183], v[64:67]
	v_mfma_f32_16x16x32_bf16 v[56:59], v[152:155], v[180:183], v[56:59]
	v_mfma_f32_16x16x32_bf16 v[48:51], v[144:147], v[188:191], v[48:51]
	v_mfma_f32_16x16x32_bf16 v[40:43], v[152:155], v[188:191], v[40:43]
	v_mfma_f32_16x16x32_bf16 v[32:35], v[144:147], v[202:205], v[32:35]
	v_mfma_f32_16x16x32_bf16 v[24:27], v[152:155], v[202:205], v[24:27]
	v_mfma_f32_16x16x32_bf16 v[16:19], v[144:147], v[210:213], v[16:19]
	v_mfma_f32_16x16x32_bf16 v[8:11], v[152:155], v[210:213], v[8:11]
	v_mfma_f32_16x16x32_bf16 v[64:67], v[148:151], v[184:187], v[64:67]
	v_mfma_f32_16x16x32_bf16 v[56:59], v[156:159], v[184:187], v[56:59]
	v_mfma_f32_16x16x32_bf16 v[48:51], v[148:151], v[192:195], v[48:51]
	v_mfma_f32_16x16x32_bf16 v[40:43], v[156:159], v[192:195], v[40:43]
	v_mfma_f32_16x16x32_bf16 v[32:35], v[148:151], v[206:209], v[32:35]
	v_mfma_f32_16x16x32_bf16 v[24:27], v[156:159], v[206:209], v[24:27]
	v_mfma_f32_16x16x32_bf16 v[16:19], v[148:151], v[214:217], v[16:19]
	v_mfma_f32_16x16x32_bf16 v[8:11], v[156:159], v[214:217], v[8:11]
	s_setprio 0
	s_setprio 3
	v_mfma_f32_16x16x32_bf16 v[60:63], v[160:163], v[180:183], v[60:63]
	v_mfma_f32_16x16x32_bf16 v[52:55], v[172:175], v[180:183], v[52:55]
	v_mfma_f32_16x16x32_bf16 v[44:47], v[160:163], v[188:191], v[44:47]
	v_mfma_f32_16x16x32_bf16 v[36:39], v[172:175], v[188:191], v[36:39]
	v_mfma_f32_16x16x32_bf16 v[28:31], v[160:163], v[202:205], v[28:31]
	v_mfma_f32_16x16x32_bf16 v[20:23], v[172:175], v[202:205], v[20:23]
	v_mfma_f32_16x16x32_bf16 v[12:15], v[160:163], v[210:213], v[12:15]
	v_mfma_f32_16x16x32_bf16 v[4:7], v[172:175], v[210:213], v[4:7]
	v_mfma_f32_16x16x32_bf16 v[60:63], v[168:171], v[184:187], v[60:63]
	v_mfma_f32_16x16x32_bf16 v[52:55], v[176:179], v[184:187], v[52:55]
	v_mfma_f32_16x16x32_bf16 v[44:47], v[168:171], v[192:195], v[44:47]
	v_mfma_f32_16x16x32_bf16 v[36:39], v[176:179], v[192:195], v[36:39]
	v_mfma_f32_16x16x32_bf16 v[28:31], v[168:171], v[206:209], v[28:31]
	v_mfma_f32_16x16x32_bf16 v[20:23], v[176:179], v[206:209], v[20:23]
	v_mfma_f32_16x16x32_bf16 v[12:15], v[168:171], v[214:217], v[12:15]
	v_mfma_f32_16x16x32_bf16 v[4:7], v[176:179], v[214:217], v[4:7]
	s_setprio 0
	s_barrier
	s_add_i32 s46, s46, 2
	s_cmp_gt_u32 s46, 13
	s_cbranch_scc0 .LBB0_405
	s_and_b64 vcc, exec, s[14:15]
	s_cbranch_vccz .LBB0_408
	s_barrier

; #define PG8_STAGE(bufoff, gbase, voff) do { _Pragma("unroll") for (int _i = 0; _i < 2; ++_i) \
;         __builtin_amdgcn_global_load_lds((const unsigned*)((const char*)(gbase) + (voff)[_i]), (PG8_LAS unsigned*)(lds + (bufoff) + ldsw + _i * 8192), 16, 0, 0); } while (0)
; #define PG8_LDA(dst, b, h) do { _Pragma("unroll") for (int m = 0; m < 4; ++m) _Pragma("unroll") for (int k = 0; k < 2; ++k) dst[m][k] = *(const PG8_LAS bf16x8*)(lds + PG8_SA(b, h) + aoff + m * 2048 + k * 1024); } while (0)
; #define PG8_LDB(dst, b, h) do { _Pragma("unroll") for (int n = 0; n < 2; ++n) _Pragma("unroll") for (int k = 0; k < 2; ++k) dst[n][k] = *(const PG8_LAS bf16x8*)(lds + PG8_SB(b, h) + boff + n * 2048 + k * 1024); } while (0)
; template <class Epi, class Sched, bool ALIGN_EPI = false, bool SP2 = false>
; __device__ __forceinline__ void gemm_phase(PG8_LAS unsigned char* lds, const Gemm g, const Sched& S, const Epi& E) {
;     ...
;         for (int t = 0; t < nt; t += 2) {
;             const bool last = (t == nt - 2);
;             const char* a1 = cA + (size_t)(t + 1) * kstep;
;             const char* a2 = last ? nA : cA + (size_t)(t + 2) * kstep; const char* b2 = last ? nB : cB + (size_t)(t + 2) * kstep;
;             const char* a3 = a2 + kstep; const char* b3 = b2 + kstep;
;             if (last && has_next) S.a_ready(nxt);
;             if constexpr (SP2) {
;             PG8_LDB(B0, 0, 0); PG8_LDB(B1, 0, 1); PG8_SCHED; PG8_LDA(At, 0, 0); PG8_STAGE(PG8_SA(1, 1), a1 + hstep, voffA);
;             PG8_WAIT_V(8); PG8_WAIT_L(0); PG8_BAR; PG8_MMA(0, 0, At, B0); PG8_MMA(0, 1, At, B1); PG8_BAR; PG8_SCHED;
;             PG8_LDA(At, 0, 1); PG8_STAGE(PG8_SB(0, 0), b2, voffB); PG8_STAGE(PG8_SB(0, 1), b2 + hstep, voffB); PG8_STAGE(PG8_SA(0, 0), a2, voffA);
;             PG8_WAIT_V(8); PG8_WAIT_L(0); PG8_BAR; PG8_MMA(1, 0, At, B0); PG8_MMA(1, 1, At, B1); PG8_BAR; PG8_SCHED;
;             PG8_LDB(B0, 1, 0); PG8_LDB(B1, 1, 1); PG8_SCHED; PG8_LDA(At, 1, 0); PG8_STAGE(PG8_SA(0, 1), a2 + hstep, voffA);
;             PG8_WAIT_V(8); PG8_WAIT_L(0); PG8_BAR; PG8_MMA(0, 0, At, B0); PG8_MMA(0, 1, At, B1); PG8_BAR; PG8_SCHED;
;             PG8_LDA(At, 1, 1); PG8_STAGE(PG8_SB(1, 0), b3, voffB); PG8_STAGE(PG8_SB(1, 1), b3 + hstep, voffB); PG8_STAGE(PG8_SA(1, 0), a3, voffA);
;             PG8_WAIT_V(8); PG8_WAIT_L(0); PG8_BAR; PG8_MMA(1, 0, At, B0); PG8_MMA(1, 1, At, B1); PG8_BAR; PG8_SCHED;
.LBB0_479:
	s_add_u32 s44, s28, 0x100
	s_addc_u32 s45, s29, 0
	s_mov_b32 s53, -2
	s_add_u32 s8, s26, 0x100
	s_addc_u32 s9, s27, 0
	s_cmp_eq_u32 s53, 40
	s_cselect_b32 s31, s23, s9
	s_cselect_b32 s30, s22, s8
	s_cselect_b32 s29, s25, s45
	s_cselect_b32 s28, s24, s44
	ds_read_b128 v[68:71], v234
	ds_read_b128 v[80:83], v234 offset:1024
	ds_read_b128 v[92:95], v234 offset:2048
	ds_read_b128 v[100:103], v234 offset:3072
	ds_read_b128 v[112:115], v234 offset:16384
	ds_read_b128 v[120:123], v234 offset:17408
	ds_read_b128 v[132:135], v234 offset:18432
	ds_read_b128 v[144:147], v234 offset:19456
	v_lshl_add_u64 v[198:199], s[26:27], 0, v[204:205]
	s_add_i32 m0, s40, 0xc000
	ds_read_b128 v[156:159], v236
	ds_read_b128 v[168:171], v236 offset:1024
	ds_read_b128 v[172:175], v236 offset:2048
	ds_read_b128 v[176:179], v236 offset:3072
	ds_read_b128 v[180:183], v236 offset:4096
	ds_read_b128 v[184:187], v236 offset:5120
	ds_read_b128 v[188:191], v236 offset:6144
	ds_read_b128 v[208:211], v236 offset:7168
	global_load_lds_dwordx4 v[198:199], off
	s_add_i32 m0, s40, 0xe000
	v_lshl_add_u64 v[198:199], s[26:27], 0, v[206:207]
	global_load_lds_dwordx4 v[198:199], off
	s_waitcnt vmcnt(8) lgkmcnt(0)
	s_barrier
	s_setprio 3
	v_mfma_f32_16x16x32_bf16 v[164:167], v[68:71], v[156:159], 0
	v_mfma_f32_16x16x32_bf16 v[160:163], v[92:95], v[156:159], 0
	v_mfma_f32_16x16x32_bf16 v[140:143], v[68:71], v[172:175], 0
	v_mfma_f32_16x16x32_bf16 v[136:139], v[92:95], v[172:175], 0
	v_mfma_f32_16x16x32_bf16 v[116:119], v[68:71], v[180:183], 0
	v_mfma_f32_16x16x32_bf16 v[108:111], v[92:95], v[180:183], 0
	v_mfma_f32_16x16x32_bf16 v[88:91], v[68:71], v[188:191], 0
	v_mfma_f32_16x16x32_bf16 v[84:87], v[92:95], v[188:191], 0
	v_mfma_f32_16x16x32_bf16 v[164:167], v[80:83], v[168:171], v[164:167]
	v_mfma_f32_16x16x32_bf16 v[160:163], v[100:103], v[168:171], v[160:163]
	v_mfma_f32_16x16x32_bf16 v[140:143], v[80:83], v[176:179], v[140:143]
	v_mfma_f32_16x16x32_bf16 v[136:139], v[100:103], v[176:179], v[136:139]
	v_mfma_f32_16x16x32_bf16 v[116:119], v[80:83], v[184:187], v[116:119]
	v_mfma_f32_16x16x32_bf16 v[108:111], v[100:103], v[184:187], v[108:111]
	v_mfma_f32_16x16x32_bf16 v[88:91], v[80:83], v[208:211], v[88:91]
	v_mfma_f32_16x16x32_bf16 v[84:87], v[100:103], v[208:211], v[84:87]
	s_setprio 0
	s_setprio 3
	v_mfma_f32_16x16x32_bf16 v[152:155], v[112:115], v[156:159], 0
	v_mfma_f32_16x16x32_bf16 v[148:151], v[132:135], v[156:159], 0
	v_mfma_f32_16x16x32_bf16 v[128:131], v[112:115], v[172:175], 0
	v_mfma_f32_16x16x32_bf16 v[124:127], v[132:135], v[172:175], 0
	v_mfma_f32_16x16x32_bf16 v[104:107], v[112:115], v[180:183], 0
	v_mfma_f32_16x16x32_bf16 v[96:99], v[132:135], v[180:183], 0
	v_mfma_f32_16x16x32_bf16 v[76:79], v[112:115], v[188:191], 0
	v_mfma_f32_16x16x32_bf16 v[72:75], v[132:135], v[188:191], 0
	v_mfma_f32_16x16x32_bf16 v[152:155], v[120:123], v[168:171], v[152:155]
	v_mfma_f32_16x16x32_bf16 v[148:151], v[144:147], v[168:171], v[148:151]
	v_mfma_f32_16x16x32_bf16 v[128:131], v[120:123], v[176:179], v[128:131]
	v_mfma_f32_16x16x32_bf16 v[124:127], v[144:147], v[176:179], v[124:127]
	v_mfma_f32_16x16x32_bf16 v[104:107], v[120:123], v[184:187], v[104:107]
	v_mfma_f32_16x16x32_bf16 v[96:99], v[144:147], v[184:187], v[96:99]
	v_mfma_f32_16x16x32_bf16 v[76:79], v[120:123], v[208:211], v[76:79]
	v_mfma_f32_16x16x32_bf16 v[72:75], v[144:147], v[208:211], v[72:75]
	s_setprio 0
	s_barrier
	v_lshl_add_u64 v[198:199], s[28:29], 0, v[192:193]
	s_add_i32 m0, s39, 0x10000
	ds_read_b128 v[156:159], v236 offset:16384
	ds_read_b128 v[168:171], v236 offset:17408
	ds_read_b128 v[172:175], v236 offset:18432
	ds_read_b128 v[176:179], v236 offset:19456
	ds_read_b128 v[180:183], v236 offset:20480
	ds_read_b128 v[184:187], v236 offset:21504
	ds_read_b128 v[188:191], v236 offset:22528
	ds_read_b128 v[208:211], v236 offset:23552
	global_load_lds_dwordx4 v[198:199], off
	s_add_i32 m0, s39, 0x12000
	s_add_u32 s26, s28, 0xb0000
	v_lshl_add_u64 v[212:213], s[28:29], 0, v[202:203]
	s_addc_u32 s27, s29, 0
	global_load_lds_dwordx4 v[212:213], off
	v_lshl_add_u64 v[244:245], s[26:27], 0, v[192:193]
	s_add_i32 m0, s39, 0x14000
	v_lshl_add_u64 v[216:217], s[30:31], 0, v[194:195]
	global_load_lds_dwordx4 v[244:245], off
	s_add_i32 m0, s39, 0x16000
	v_lshl_add_u64 v[246:247], s[26:27], 0, v[202:203]
	global_load_lds_dwordx4 v[246:247], off
	v_lshl_add_u64 v[214:215], s[30:31], 0, v[0:1]
	s_waitcnt vmcnt(6) lgkmcnt(0)
	s_barrier
	s_setprio 3
	v_mfma_f32_16x16x32_bf16 v[64:67], v[68:71], v[156:159], 0
	v_mfma_f32_16x16x32_bf16 v[60:63], v[92:95], v[156:159], 0
	v_mfma_f32_16x16x32_bf16 v[48:51], v[68:71], v[172:175], 0
	v_mfma_f32_16x16x32_bf16 v[44:47], v[92:95], v[172:175], 0
	v_mfma_f32_16x16x32_bf16 v[32:35], v[68:71], v[180:183], 0
	v_mfma_f32_16x16x32_bf16 v[28:31], v[92:95], v[180:183], 0
	v_mfma_f32_16x16x32_bf16 v[16:19], v[68:71], v[188:191], 0
	v_mfma_f32_16x16x32_bf16 v[12:15], v[92:95], v[188:191], 0
	v_mfma_f32_16x16x32_bf16 v[64:67], v[80:83], v[168:171], v[64:67]
	v_mfma_f32_16x16x32_bf16 v[60:63], v[100:103], v[168:171], v[60:63]
	v_mfma_f32_16x16x32_bf16 v[48:51], v[80:83], v[176:179], v[48:51]
	v_mfma_f32_16x16x32_bf16 v[44:47], v[100:103], v[176:179], v[44:47]
	v_mfma_f32_16x16x32_bf16 v[32:35], v[80:83], v[184:187], v[32:35]
	v_mfma_f32_16x16x32_bf16 v[28:31], v[100:103], v[184:187], v[28:31]
	v_mfma_f32_16x16x32_bf16 v[16:19], v[80:83], v[208:211], v[16:19]
	v_mfma_f32_16x16x32_bf16 v[12:15], v[100:103], v[208:211], v[12:15]
	s_setprio 0
	s_setprio 3
	v_mfma_f32_16x16x32_bf16 v[56:59], v[112:115], v[156:159], 0
	v_mfma_f32_16x16x32_bf16 v[52:55], v[132:135], v[156:159], 0
	v_mfma_f32_16x16x32_bf16 v[40:43], v[112:115], v[172:175], 0
	v_mfma_f32_16x16x32_bf16 v[36:39], v[132:135], v[172:175], 0
	v_mfma_f32_16x16x32_bf16 v[24:27], v[112:115], v[180:183], 0
	v_mfma_f32_16x16x32_bf16 v[20:23], v[132:135], v[180:183], 0
	v_mfma_f32_16x16x32_bf16 v[8:11], v[112:115], v[188:191], 0
	v_mfma_f32_16x16x32_bf16 v[4:7], v[132:135], v[188:191], 0
	v_mfma_f32_16x16x32_bf16 v[56:59], v[120:123], v[168:171], v[56:59]
	v_mfma_f32_16x16x32_bf16 v[52:55], v[144:147], v[168:171], v[52:55]
	v_mfma_f32_16x16x32_bf16 v[40:43], v[120:123], v[176:179], v[40:43]
	v_mfma_f32_16x16x32_bf16 v[36:39], v[144:147], v[176:179], v[36:39]
	v_mfma_f32_16x16x32_bf16 v[24:27], v[120:123], v[184:187], v[24:27]
	v_mfma_f32_16x16x32_bf16 v[20:23], v[144:147], v[184:187], v[20:23]
	v_mfma_f32_16x16x32_bf16 v[8:11], v[120:123], v[208:211], v[8:11]
	v_mfma_f32_16x16x32_bf16 v[4:7], v[144:147], v[208:211], v[4:7]
	s_setprio 0
	s_barrier
	s_branch .Lkmid_3
; #define PG8_STAGE(bufoff, gbase, voff) do { _Pragma("unroll") for (int _i = 0; _i < 2; ++_i) \
;         __builtin_amdgcn_global_load_lds((const unsigned*)((const char*)(gbase) + (voff)[_i]), (PG8_LAS unsigned*)(lds + (bufoff) + ldsw + _i * 8192), 16, 0, 0); } while (0)
; #define PG8_LDA(dst, b, h) do { _Pragma("unroll") for (int m = 0; m < 4; ++m) _Pragma("unroll") for (int k = 0; k < 2; ++k) dst[m][k] = *(const PG8_LAS bf16x8*)(lds + PG8_SA(b, h) + aoff + m * 2048 + k * 1024); } while (0)
; #define PG8_LDB(dst, b, h) do { _Pragma("unroll") for (int n = 0; n < 2; ++n) _Pragma("unroll") for (int k = 0; k < 2; ++k) dst[n][k] = *(const PG8_LAS bf16x8*)(lds + PG8_SB(b, h) + boff + n * 2048 + k * 1024); } while (0)
; #define PG8_MMA(ai, bj, At, Bt) do { __builtin_amdgcn_s_setprio(1); _Pragma("unroll") for (int m = 0; m < 4; ++m) _Pragma("unroll") for (int n = 0; n < 2; ++n) _Pragma("unroll") for (int k = 0; k < 2; ++k) \
;         acc[ai][bj][m][n] = __builtin_amdgcn_mfma_f32_16x16x32_bf16(Bt[n][k], At[m][k], acc[ai][bj][m][n], 0, 0, 0); __builtin_amdgcn_s_setprio(0); } while (0)
; #define PG8_WAIT_V(n) asm volatile("s_waitcnt vmcnt(" #n ")" ::: "memory")
; #define PG8_WAIT_L(n) asm volatile("s_waitcnt lgkmcnt(" #n ")" ::: "memory")
; #define PG8_BAR __builtin_amdgcn_s_barrier()
; #define PG8_SCHED __builtin_amdgcn_sched_barrier(0)
; template <class Epi, class Sched, bool ALIGN_EPI = false, bool SP2 = false>
; __device__ __forceinline__ void gemm_phase(PG8_LAS unsigned char* lds, const Gemm g, const Sched& S, const Epi& E) {
;     ...
;             PG8_LDB(B0, 0, 0); PG8_LDB(B1, 0, 1); PG8_SCHED; PG8_LDA(At, 0, 0); PG8_STAGE(PG8_SA(1, 1), a1 + hstep, voffA);
;             PG8_WAIT_V(8); PG8_WAIT_L(0); PG8_BAR; PG8_MMA(0, 0, At, B0); PG8_MMA(0, 1, At, B1); PG8_BAR; PG8_SCHED;
;             PG8_LDA(At, 0, 1); PG8_STAGE(PG8_SB(0, 0), b2, voffB); PG8_STAGE(PG8_SB(0, 1), b2 + hstep, voffB); PG8_STAGE(PG8_SA(0, 0), a2, voffA);
;             PG8_WAIT_V(8); PG8_WAIT_L(0); PG8_BAR; PG8_MMA(1, 0, At, B0); PG8_MMA(1, 1, At, B1); PG8_BAR; PG8_SCHED;
.LBB0_480:
	s_add_u32 s8, s26, 0x100
	s_addc_u32 s9, s27, 0
	s_cmp_eq_u32 s53, 40
	s_cselect_b32 s31, s23, s9
	s_cselect_b32 s30, s22, s8
	s_cselect_b32 s29, s25, s45
	s_cselect_b32 s28, s24, s44
	s_add_i32 m0, s47, 0xffffff80
	ds_read_b128 v[68:71], v234
	ds_read_b128 v[80:83], v234 offset:1024
	ds_read_b128 v[92:95], v234 offset:2048
	ds_read_b128 v[100:103], v234 offset:3072
	ds_read_b128 v[112:115], v234 offset:16384
	ds_read_b128 v[120:123], v234 offset:17408
	ds_read_b128 v[132:135], v234 offset:18432
	ds_read_b128 v[144:147], v234 offset:19456
	global_load_lds_dwordx4 v[214:215], off offset:128
	s_add_i32 m0, s48, 0xffffff80
	v_lshl_add_u64 v[198:199], s[26:27], 0, v[204:205]
	global_load_lds_dwordx4 v[216:217], off offset:128
	s_add_i32 m0, s40, 0xc000
	ds_read_b128 v[156:159], v236
	ds_read_b128 v[168:171], v236 offset:1024
	ds_read_b128 v[172:175], v236 offset:2048
	ds_read_b128 v[176:179], v236 offset:3072
	ds_read_b128 v[180:183], v236 offset:4096
	ds_read_b128 v[184:187], v236 offset:5120
	ds_read_b128 v[188:191], v236 offset:6144
	ds_read_b128 v[208:211], v236 offset:7168
	global_load_lds_dwordx4 v[198:199], off
	s_add_i32 m0, s40, 0xe000
	v_lshl_add_u64 v[198:199], s[26:27], 0, v[206:207]
	global_load_lds_dwordx4 v[198:199], off
	s_waitcnt vmcnt(8) lgkmcnt(0)
	s_barrier
	s_setprio 3
	v_mfma_f32_16x16x32_bf16 v[164:167], v[68:71], v[156:159], v[164:167]
	v_mfma_f32_16x16x32_bf16 v[160:163], v[92:95], v[156:159], v[160:163]
	v_mfma_f32_16x16x32_bf16 v[140:143], v[68:71], v[172:175], v[140:143]
	v_mfma_f32_16x16x32_bf16 v[136:139], v[92:95], v[172:175], v[136:139]
	v_mfma_f32_16x16x32_bf16 v[116:119], v[68:71], v[180:183], v[116:119]
	v_mfma_f32_16x16x32_bf16 v[108:111], v[92:95], v[180:183], v[108:111]
	v_mfma_f32_16x16x32_bf16 v[88:91], v[68:71], v[188:191], v[88:91]
	v_mfma_f32_16x16x32_bf16 v[84:87], v[92:95], v[188:191], v[84:87]
	v_mfma_f32_16x16x32_bf16 v[164:167], v[80:83], v[168:171], v[164:167]
	v_mfma_f32_16x16x32_bf16 v[160:163], v[100:103], v[168:171], v[160:163]
	v_mfma_f32_16x16x32_bf16 v[140:143], v[80:83], v[176:179], v[140:143]
	v_mfma_f32_16x16x32_bf16 v[136:139], v[100:103], v[176:179], v[136:139]
	v_mfma_f32_16x16x32_bf16 v[116:119], v[80:83], v[184:187], v[116:119]
	v_mfma_f32_16x16x32_bf16 v[108:111], v[100:103], v[184:187], v[108:111]
	v_mfma_f32_16x16x32_bf16 v[88:91], v[80:83], v[208:211], v[88:91]
	v_mfma_f32_16x16x32_bf16 v[84:87], v[100:103], v[208:211], v[84:87]
	s_setprio 0
	s_setprio 3
	v_mfma_f32_16x16x32_bf16 v[152:155], v[112:115], v[156:159], v[152:155]
	v_mfma_f32_16x16x32_bf16 v[148:151], v[132:135], v[156:159], v[148:151]
	v_mfma_f32_16x16x32_bf16 v[128:131], v[112:115], v[172:175], v[128:131]
	v_mfma_f32_16x16x32_bf16 v[124:127], v[132:135], v[172:175], v[124:127]
	v_mfma_f32_16x16x32_bf16 v[104:107], v[112:115], v[180:183], v[104:107]
	v_mfma_f32_16x16x32_bf16 v[96:99], v[132:135], v[180:183], v[96:99]
	v_mfma_f32_16x16x32_bf16 v[76:79], v[112:115], v[188:191], v[76:79]
	v_mfma_f32_16x16x32_bf16 v[72:75], v[132:135], v[188:191], v[72:75]
	v_mfma_f32_16x16x32_bf16 v[152:155], v[120:123], v[168:171], v[152:155]
	v_mfma_f32_16x16x32_bf16 v[148:151], v[144:147], v[168:171], v[148:151]
	v_mfma_f32_16x16x32_bf16 v[128:131], v[120:123], v[176:179], v[128:131]
	v_mfma_f32_16x16x32_bf16 v[124:127], v[144:147], v[176:179], v[124:127]
	v_mfma_f32_16x16x32_bf16 v[104:107], v[120:123], v[184:187], v[104:107]
	v_mfma_f32_16x16x32_bf16 v[96:99], v[144:147], v[184:187], v[96:99]
	v_mfma_f32_16x16x32_bf16 v[76:79], v[120:123], v[208:211], v[76:79]
	v_mfma_f32_16x16x32_bf16 v[72:75], v[144:147], v[208:211], v[72:75]
	s_setprio 0
	s_barrier
	v_lshl_add_u64 v[198:199], s[28:29], 0, v[192:193]
	s_add_i32 m0, s39, 0x10000
	ds_read_b128 v[156:159], v236 offset:16384
	ds_read_b128 v[168:171], v236 offset:17408
	ds_read_b128 v[172:175], v236 offset:18432
	ds_read_b128 v[176:179], v236 offset:19456
	ds_read_b128 v[180:183], v236 offset:20480
	ds_read_b128 v[184:187], v236 offset:21504
	ds_read_b128 v[188:191], v236 offset:22528
	ds_read_b128 v[208:211], v236 offset:23552
	global_load_lds_dwordx4 v[198:199], off
	s_add_i32 m0, s39, 0x12000
	s_add_u32 s26, s28, 0xb0000
	v_lshl_add_u64 v[212:213], s[28:29], 0, v[202:203]
	s_addc_u32 s27, s29, 0
	global_load_lds_dwordx4 v[212:213], off
	v_lshl_add_u64 v[244:245], s[26:27], 0, v[192:193]
	s_add_i32 m0, s39, 0x14000
	v_lshl_add_u64 v[216:217], s[30:31], 0, v[194:195]
	global_load_lds_dwordx4 v[244:245], off
	s_add_i32 m0, s39, 0x16000
	v_lshl_add_u64 v[246:247], s[26:27], 0, v[202:203]
	global_load_lds_dwordx4 v[246:247], off
	v_lshl_add_u64 v[214:215], s[30:31], 0, v[0:1]
	s_waitcnt vmcnt(6) lgkmcnt(0)
	s_barrier
	s_setprio 3
	v_mfma_f32_16x16x32_bf16 v[64:67], v[68:71], v[156:159], v[64:67]
	v_mfma_f32_16x16x32_bf16 v[60:63], v[92:95], v[156:159], v[60:63]
	v_mfma_f32_16x16x32_bf16 v[48:51], v[68:71], v[172:175], v[48:51]
	v_mfma_f32_16x16x32_bf16 v[44:47], v[92:95], v[172:175], v[44:47]
	v_mfma_f32_16x16x32_bf16 v[32:35], v[68:71], v[180:183], v[32:35]
	v_mfma_f32_16x16x32_bf16 v[28:31], v[92:95], v[180:183], v[28:31]
	v_mfma_f32_16x16x32_bf16 v[16:19], v[68:71], v[188:191], v[16:19]
	v_mfma_f32_16x16x32_bf16 v[12:15], v[92:95], v[188:191], v[12:15]
	v_mfma_f32_16x16x32_bf16 v[64:67], v[80:83], v[168:171], v[64:67]
	v_mfma_f32_16x16x32_bf16 v[60:63], v[100:103], v[168:171], v[60:63]
	v_mfma_f32_16x16x32_bf16 v[48:51], v[80:83], v[176:179], v[48:51]
	v_mfma_f32_16x16x32_bf16 v[44:47], v[100:103], v[176:179], v[44:47]
	v_mfma_f32_16x16x32_bf16 v[32:35], v[80:83], v[184:187], v[32:35]
	v_mfma_f32_16x16x32_bf16 v[28:31], v[100:103], v[184:187], v[28:31]
	v_mfma_f32_16x16x32_bf16 v[16:19], v[80:83], v[208:211], v[16:19]
	v_mfma_f32_16x16x32_bf16 v[12:15], v[100:103], v[208:211], v[12:15]
	s_setprio 0
	s_setprio 3
	v_mfma_f32_16x16x32_bf16 v[56:59], v[112:115], v[156:159], v[56:59]
	v_mfma_f32_16x16x32_bf16 v[52:55], v[132:135], v[156:159], v[52:55]
	v_mfma_f32_16x16x32_bf16 v[40:43], v[112:115], v[172:175], v[40:43]
	v_mfma_f32_16x16x32_bf16 v[36:39], v[132:135], v[172:175], v[36:39]
	v_mfma_f32_16x16x32_bf16 v[24:27], v[112:115], v[180:183], v[24:27]
	v_mfma_f32_16x16x32_bf16 v[20:23], v[132:135], v[180:183], v[20:23]
	v_mfma_f32_16x16x32_bf16 v[8:11], v[112:115], v[188:191], v[8:11]
	v_mfma_f32_16x16x32_bf16 v[4:7], v[132:135], v[188:191], v[4:7]
	v_mfma_f32_16x16x32_bf16 v[56:59], v[120:123], v[168:171], v[56:59]
	v_mfma_f32_16x16x32_bf16 v[52:55], v[144:147], v[168:171], v[52:55]
	v_mfma_f32_16x16x32_bf16 v[40:43], v[120:123], v[176:179], v[40:43]
	v_mfma_f32_16x16x32_bf16 v[36:39], v[144:147], v[176:179], v[36:39]
	v_mfma_f32_16x16x32_bf16 v[24:27], v[120:123], v[184:187], v[24:27]
	v_mfma_f32_16x16x32_bf16 v[20:23], v[144:147], v[184:187], v[20:23]
	v_mfma_f32_16x16x32_bf16 v[8:11], v[120:123], v[208:211], v[8:11]
	v_mfma_f32_16x16x32_bf16 v[4:7], v[144:147], v[208:211], v[4:7]
	s_setprio 0
	s_barrier
; #define PG8_STAGE(bufoff, gbase, voff) do { _Pragma("unroll") for (int _i = 0; _i < 2; ++_i) \
;         __builtin_amdgcn_global_load_lds((const unsigned*)((const char*)(gbase) + (voff)[_i]), (PG8_LAS unsigned*)(lds + (bufoff) + ldsw + _i * 8192), 16, 0, 0); } while (0)
; #define PG8_LDA(dst, b, h) do { _Pragma("unroll") for (int m = 0; m < 4; ++m) _Pragma("unroll") for (int k = 0; k < 2; ++k) dst[m][k] = *(const PG8_LAS bf16x8*)(lds + PG8_SA(b, h) + aoff + m * 2048 + k * 1024); } while (0)
; #define PG8_LDB(dst, b, h) do { _Pragma("unroll") for (int n = 0; n < 2; ++n) _Pragma("unroll") for (int k = 0; k < 2; ++k) dst[n][k] = *(const PG8_LAS bf16x8*)(lds + PG8_SB(b, h) + boff + n * 2048 + k * 1024); } while (0)
; #define PG8_MMA(ai, bj, At, Bt) do { __builtin_amdgcn_s_setprio(1); _Pragma("unroll") for (int m = 0; m < 4; ++m) _Pragma("unroll") for (int n = 0; n < 2; ++n) _Pragma("unroll") for (int k = 0; k < 2; ++k) \
;         acc[ai][bj][m][n] = __builtin_amdgcn_mfma_f32_16x16x32_bf16(Bt[n][k], At[m][k], acc[ai][bj][m][n], 0, 0, 0); __builtin_amdgcn_s_setprio(0); } while (0)
; #define PG8_WAIT_V(n) asm volatile("s_waitcnt vmcnt(" #n ")" ::: "memory")
; #define PG8_WAIT_L(n) asm volatile("s_waitcnt lgkmcnt(" #n ")" ::: "memory")
; #define PG8_BAR __builtin_amdgcn_s_barrier()
; #define PG8_SCHED __builtin_amdgcn_sched_barrier(0)
; template <class Epi, class Sched, bool ALIGN_EPI = false, bool SP2 = false>
; __device__ __forceinline__ void gemm_phase(PG8_LAS unsigned char* lds, const Gemm g, const Sched& S, const Epi& E) {
;     ...
;         for (int t = 0; t < nt; t += 2) {
;             const bool last = (t == nt - 2);
;             const char* a1 = cA + (size_t)(t + 1) * kstep;
;             const char* a2 = last ? nA : cA + (size_t)(t + 2) * kstep; const char* b2 = last ? nB : cB + (size_t)(t + 2) * kstep;
;     ...
;             PG8_LDB(B0, 1, 0); PG8_LDB(B1, 1, 1); PG8_SCHED; PG8_LDA(At, 1, 0); PG8_STAGE(PG8_SA(0, 1), a2 + hstep, voffA);
;             PG8_WAIT_V(8); PG8_WAIT_L(0); PG8_BAR; PG8_MMA(0, 0, At, B0); PG8_MMA(0, 1, At, B1); PG8_BAR; PG8_SCHED;
;             PG8_LDA(At, 1, 1); PG8_STAGE(PG8_SB(1, 0), b3, voffB); PG8_STAGE(PG8_SB(1, 1), b3 + hstep, voffB); PG8_STAGE(PG8_SA(1, 0), a3, voffA);
;             PG8_WAIT_V(8); PG8_WAIT_L(0); PG8_BAR; PG8_MMA(1, 0, At, B0); PG8_MMA(1, 1, At, B1); PG8_BAR; PG8_SCHED;
.Lkmid_3:
	ds_read_b128 v[68:71], v234 offset:32768
	ds_read_b128 v[80:83], v234 offset:33792
	ds_read_b128 v[92:95], v234 offset:34816
	ds_read_b128 v[100:103], v234 offset:35840
	ds_read_b128 v[112:115], v234 offset:49152
	ds_read_b128 v[120:123], v234 offset:50176
	ds_read_b128 v[132:135], v234 offset:51200
	ds_read_b128 v[144:147], v234 offset:52224
	s_mov_b32 m0, s40
	s_add_u32 s26, s30, 0xb0000
	s_addc_u32 s27, s31, 0
	global_load_lds_dwordx4 v[214:215], off
	s_mov_b32 m0, s41
	v_lshl_add_u64 v[218:219], s[26:27], 0, v[0:1]
	global_load_lds_dwordx4 v[216:217], off
	s_mov_b32 m0, s42
	ds_read_b128 v[156:159], v236 offset:32768
	ds_read_b128 v[168:171], v236 offset:33792
	ds_read_b128 v[172:175], v236 offset:34816
	ds_read_b128 v[176:179], v236 offset:35840
	ds_read_b128 v[180:183], v236 offset:36864
	ds_read_b128 v[184:187], v236 offset:37888
	ds_read_b128 v[188:191], v236 offset:38912
	ds_read_b128 v[208:211], v236 offset:39936
	global_load_lds_dwordx4 v[218:219], off
	s_mov_b32 m0, s43
	v_lshl_add_u64 v[218:219], s[26:27], 0, v[194:195]
	global_load_lds_dwordx4 v[218:219], off
	s_waitcnt vmcnt(8) lgkmcnt(0)
	s_barrier
	s_setprio 3
	v_mfma_f32_16x16x32_bf16 v[164:167], v[68:71], v[156:159], v[164:167]
	v_mfma_f32_16x16x32_bf16 v[160:163], v[92:95], v[156:159], v[160:163]
	v_mfma_f32_16x16x32_bf16 v[140:143], v[68:71], v[172:175], v[140:143]
	v_mfma_f32_16x16x32_bf16 v[136:139], v[92:95], v[172:175], v[136:139]
	v_mfma_f32_16x16x32_bf16 v[116:119], v[68:71], v[180:183], v[116:119]
	v_mfma_f32_16x16x32_bf16 v[108:111], v[92:95], v[180:183], v[108:111]
	v_mfma_f32_16x16x32_bf16 v[88:91], v[68:71], v[188:191], v[88:91]
	v_mfma_f32_16x16x32_bf16 v[84:87], v[92:95], v[188:191], v[84:87]
	v_mfma_f32_16x16x32_bf16 v[164:167], v[80:83], v[168:171], v[164:167]
	v_mfma_f32_16x16x32_bf16 v[160:163], v[100:103], v[168:171], v[160:163]
	v_mfma_f32_16x16x32_bf16 v[140:143], v[80:83], v[176:179], v[140:143]
	v_mfma_f32_16x16x32_bf16 v[136:139], v[100:103], v[176:179], v[136:139]
	v_mfma_f32_16x16x32_bf16 v[116:119], v[80:83], v[184:187], v[116:119]
	v_mfma_f32_16x16x32_bf16 v[108:111], v[100:103], v[184:187], v[108:111]
	v_mfma_f32_16x16x32_bf16 v[88:91], v[80:83], v[208:211], v[88:91]
	v_mfma_f32_16x16x32_bf16 v[84:87], v[100:103], v[208:211], v[84:87]
	s_setprio 0
	s_setprio 3
	v_mfma_f32_16x16x32_bf16 v[152:155], v[112:115], v[156:159], v[152:155]
	v_mfma_f32_16x16x32_bf16 v[148:151], v[132:135], v[156:159], v[148:151]
	v_mfma_f32_16x16x32_bf16 v[128:131], v[112:115], v[172:175], v[128:131]
	v_mfma_f32_16x16x32_bf16 v[124:127], v[132:135], v[172:175], v[124:127]
	v_mfma_f32_16x16x32_bf16 v[104:107], v[112:115], v[180:183], v[104:107]
	v_mfma_f32_16x16x32_bf16 v[96:99], v[132:135], v[180:183], v[96:99]
	v_mfma_f32_16x16x32_bf16 v[76:79], v[112:115], v[188:191], v[76:79]
	v_mfma_f32_16x16x32_bf16 v[72:75], v[132:135], v[188:191], v[72:75]
	v_mfma_f32_16x16x32_bf16 v[152:155], v[120:123], v[168:171], v[152:155]
	v_mfma_f32_16x16x32_bf16 v[148:151], v[144:147], v[168:171], v[148:151]
	v_mfma_f32_16x16x32_bf16 v[128:131], v[120:123], v[176:179], v[128:131]
	v_mfma_f32_16x16x32_bf16 v[124:127], v[144:147], v[176:179], v[124:127]
	v_mfma_f32_16x16x32_bf16 v[104:107], v[120:123], v[184:187], v[104:107]
	v_mfma_f32_16x16x32_bf16 v[96:99], v[144:147], v[184:187], v[96:99]
	v_mfma_f32_16x16x32_bf16 v[76:79], v[120:123], v[208:211], v[76:79]
	v_mfma_f32_16x16x32_bf16 v[72:75], v[144:147], v[208:211], v[72:75]
	s_setprio 0
	s_barrier
	s_add_i32 m0, s39, 0x17f80
	ds_read_b128 v[156:159], v236 offset:49152
	ds_read_b128 v[168:171], v236 offset:50176
	ds_read_b128 v[172:175], v236 offset:51200
	ds_read_b128 v[176:179], v236 offset:52224
	ds_read_b128 v[180:183], v236 offset:53248
	ds_read_b128 v[184:187], v236 offset:54272
	ds_read_b128 v[188:191], v236 offset:55296
	ds_read_b128 v[208:211], v236 offset:56320
	global_load_lds_dwordx4 v[198:199], off offset:128
	s_add_i32 m0, s39, 0x19f80
	s_mov_b64 s[26:27], s[8:9]
	global_load_lds_dwordx4 v[212:213], off offset:128
	s_add_i32 m0, s39, 0x1bf80
	s_add_u32 s44, s44, 0x100
	s_addc_u32 s45, s45, 0
	global_load_lds_dwordx4 v[244:245], off offset:128
	s_add_i32 m0, s39, 0x1df80
	s_cmp_eq_u32 s53, 40
	global_load_lds_dwordx4 v[246:247], off offset:128
	s_cbranch_scc0 .Lks4_3
	s_add_i32 m0, s47, 0xffffff80
	s_nop 0
	global_load_lds_dwordx4 v[214:215], off offset:128
	s_add_i32 m0, s48, 0xffffff80
	s_nop 0
	global_load_lds_dwordx4 v[216:217], off offset:128
.Lks4_3:
	s_waitcnt vmcnt(6) lgkmcnt(0)
	s_barrier
	s_setprio 3
	v_mfma_f32_16x16x32_bf16 v[64:67], v[68:71], v[156:159], v[64:67]
	v_mfma_f32_16x16x32_bf16 v[60:63], v[92:95], v[156:159], v[60:63]
	v_mfma_f32_16x16x32_bf16 v[48:51], v[68:71], v[172:175], v[48:51]
	v_mfma_f32_16x16x32_bf16 v[44:47], v[92:95], v[172:175], v[44:47]
	v_mfma_f32_16x16x32_bf16 v[32:35], v[68:71], v[180:183], v[32:35]
	v_mfma_f32_16x16x32_bf16 v[28:31], v[92:95], v[180:183], v[28:31]
	v_mfma_f32_16x16x32_bf16 v[16:19], v[68:71], v[188:191], v[16:19]
	v_mfma_f32_16x16x32_bf16 v[12:15], v[92:95], v[188:191], v[12:15]
	v_mfma_f32_16x16x32_bf16 v[64:67], v[80:83], v[168:171], v[64:67]
	v_mfma_f32_16x16x32_bf16 v[60:63], v[100:103], v[168:171], v[60:63]
	v_mfma_f32_16x16x32_bf16 v[48:51], v[80:83], v[176:179], v[48:51]
	v_mfma_f32_16x16x32_bf16 v[44:47], v[100:103], v[176:179], v[44:47]
	v_mfma_f32_16x16x32_bf16 v[32:35], v[80:83], v[184:187], v[32:35]
	v_mfma_f32_16x16x32_bf16 v[28:31], v[100:103], v[184:187], v[28:31]
	v_mfma_f32_16x16x32_bf16 v[16:19], v[80:83], v[208:211], v[16:19]
	v_mfma_f32_16x16x32_bf16 v[12:15], v[100:103], v[208:211], v[12:15]
	s_setprio 0
	s_setprio 3
	v_mfma_f32_16x16x32_bf16 v[56:59], v[112:115], v[156:159], v[56:59]
	v_mfma_f32_16x16x32_bf16 v[52:55], v[132:135], v[156:159], v[52:55]
	v_mfma_f32_16x16x32_bf16 v[40:43], v[112:115], v[172:175], v[40:43]
	v_mfma_f32_16x16x32_bf16 v[36:39], v[132:135], v[172:175], v[36:39]
	v_mfma_f32_16x16x32_bf16 v[24:27], v[112:115], v[180:183], v[24:27]
	v_mfma_f32_16x16x32_bf16 v[20:23], v[132:135], v[180:183], v[20:23]
	v_mfma_f32_16x16x32_bf16 v[8:11], v[112:115], v[188:191], v[8:11]
	v_mfma_f32_16x16x32_bf16 v[4:7], v[132:135], v[188:191], v[4:7]
	v_mfma_f32_16x16x32_bf16 v[56:59], v[120:123], v[168:171], v[56:59]
	v_mfma_f32_16x16x32_bf16 v[52:55], v[144:147], v[168:171], v[52:55]
	v_mfma_f32_16x16x32_bf16 v[40:43], v[120:123], v[176:179], v[40:43]
	v_mfma_f32_16x16x32_bf16 v[36:39], v[144:147], v[176:179], v[36:39]
	v_mfma_f32_16x16x32_bf16 v[24:27], v[120:123], v[184:187], v[24:27]
	v_mfma_f32_16x16x32_bf16 v[20:23], v[144:147], v[184:187], v[20:23]
	v_mfma_f32_16x16x32_bf16 v[8:11], v[120:123], v[208:211], v[8:11]
	v_mfma_f32_16x16x32_bf16 v[4:7], v[144:147], v[208:211], v[4:7]
	s_setprio 0
	s_barrier
	s_add_i32 s53, s53, 2
	s_cmp_gt_u32 s53, 41
	s_cbranch_scc0 .LBB0_480
	s_and_b64 vcc, exec, s[20:21]
	s_cbranch_vccz .LBB0_483
	s_barrier
